# G2 K-loop: direct global->LDS loads (global_load_lds_dwordx4) replace VGPR staging + ds_write_b128; LDS image shifted 1 KiB so M0 absorbs the instruction offsets; SCC recomputed before the back edge
# speedup vs baseline: 1.0209x; 1.0064x over previous
; __device__ __forceinline__ int otid() { int t = threadIdx.x; asm volatile("" : "+v"(t)); return t; }
; template <bool DEEP>
; __device__ __forceinline__ void gemm_core(const bf16_t* __restrict__ A, int lda, const bf16_t* __restrict__ Bt, int ldb,
;                                           int K, f32x4 (&acc)[4][4], char* smem) {
;   bf16_t* sA = (bf16_t*)smem;
;   bf16_t* sB = sA + 2 * 128 * LDS_STRIDE;
;   const int tid = otid(), lane = tid & 63, wave = tid >> 6;
;   const int wm = wave >> 1, wn = wave & 1;
;   const int lr = tid >> 3, lc = (tid & 7) * 8;
;   const bf16_t* ap = A + (size_t)lr * lda + lc;
;   const bf16_t* bp = Bt + (size_t)lr * ldb + lc;
;   const int nk = K >> 6;
;   const int fr = lane & 15, fq = (lane >> 4) * 8;
;   const int rswz = (fr >> 1) & 7, wswz = (lr >> 1) & 7;
;   const int fo0 = (((lane >> 4)) ^ rswz) * 8, fo1 = ((4 + (lane >> 4)) ^ rswz) * 8;
;   const bf16_t* cA0 = sA + (wm * 64 + fr) * LDS_STRIDE;
;   const bf16_t* cB0 = sB + (wn * 64 + fr) * LDS_STRIDE;
;   bf16_t* wA = sA + lr * LDS_STRIDE + (((tid & 7) ^ wswz) * 8);
;   bf16_t* wB = sB + lr * LDS_STRIDE + (((tid & 7) ^ wswz) * 8);
;   constexpr int BUF = 128 * LDS_STRIDE;
;     ...
;   u32x4 ra0[4], rb0[4];
;   GLOAD(ra0, rb0, 0);
;   if (DEEP) {
;     u32x4 ra1[4], rb1[4];
;     GLOAD(ra1, rb1, 1);
;     __syncthreads();
;     SWRITE(ra0, rb0, 0);
;     __syncthreads();
;     for (int kt = 0; kt < nk; kt += 2) {
;       { const int k2 = min(kt + 2, nk - 1); GLOAD(ra0, rb0, k2); }
;       mma_ktile(cA0, cB0, fo0, fo1, acc);
;       SWRITE(ra1, rb1, 1);
;       __syncthreads();
;       { const int k3 = min(kt + 3, nk - 1); GLOAD(ra1, rb1, k3); }
;       mma_ktile(cA0 + BUF, cB0 + BUF, fo0, fo1, acc);
;       if (kt + 2 < nk) { SWRITE(ra0, rb0, 0); }
;       __syncthreads();
;     }
;   } else {
;     __syncthreads();
;     SWRITE(ra0, rb0, 0);
;     __syncthreads();
;     for (int kt = 0; kt < nk; ++kt) {
;       const int cur = kt & 1;
;       { const int k1 = min(kt + 1, nk - 1); GLOAD(ra0, rb0, k1); }
;       mma_ktile(cA0 + cur * BUF, cB0 + cur * BUF, fo0, fo1, acc);
;       if (kt + 1 < nk) { SWRITE(ra0, rb0, cur ^ 1); }
;       __syncthreads();
.LBB0_21:
	v_mov_b32_e32 v128, v178
	v_lshrrev_b32_e32 v177, 6, v178
	v_lshlrev_b32_e32 v177, 10, v177
	v_add_u32_e32 v177, 0x400, v177
	s_mov_b32 s29, 0x237f8000
	v_ashrrev_i32_e32 v126, 3, v128
	v_mad_i64_i32 v[4:5], s[30:31], v126, s78, 0
	v_lshrrev_b32_e32 v187, 4, v128
	v_xor_b32_e32 v187, v187, v128
	v_lshlrev_b32_e32 v6, 4, v187
	v_and_b32_e32 v6, 0x70, v6
	s_add_u32 s30, s13, s16
	v_ashrrev_i32_e32 v127, 31, v126
	v_or_b32_e32 v4, v4, v6
	s_addc_u32 s31, s28, s17
	v_lshl_add_u64 v[36:37], s[30:31], 0, v[4:5]
	v_lshlrev_b64 v[4:5], 10, v[126:127]
	s_add_u32 s30, s10, s14
	v_or_b32_e32 v4, v4, v6
	s_addc_u32 s31, s11, s15
	v_lshl_add_u64 v[32:33], s[30:31], 0, v[4:5]
	v_add_co_u32_e32 v38, vcc, s29, v32
	s_mov_b32 s29, 0x23800000
	s_nop 0
	v_addc_co_u32_e32 v39, vcc, 0, v33, vcc
	v_add_co_u32_e32 v40, vcc, s1, v36
	v_and_b32_e32 v4, 15, v128
	s_nop 0
	v_addc_co_u32_e32 v41, vcc, 0, v37, vcc
	v_add_co_u32_e32 v42, vcc, s29, v32
	v_lshrrev_b32_e32 v7, 1, v128
	s_nop 0
	v_addc_co_u32_e32 v43, vcc, 0, v33, vcc
	v_lshrrev_b32_e32 v5, 4, v128
	v_bfe_u32 v6, v128, 4, 2
	v_bfe_u32 v8, v128, 1, 3
	v_and_or_b32 v4, v7, s79, v4
	v_add_co_u32_e32 v44, vcc, s0, v36
	v_bitop3_b32 v127, v5, v8, 3 bitop3:0x6c
	v_bitop3_b32 v129, v6, v8, 4 bitop3:0x36
	v_lshlrev_b32_e32 v130, 7, v4
	v_xor_b32_e32 v131, v5, v128
	v_addc_co_u32_e32 v45, vcc, 0, v37, vcc
	s_mov_b32 s29, 0x23808000
	v_add_co_u32_e32 v46, vcc, s29, v32
	s_nop 0
	v_addc_co_u32_e32 v47, vcc, 0, v33, vcc
	s_mov_b32 s29, 0x48000
	v_add_co_u32_e32 v48, vcc, s29, v36
	s_nop 0
	v_addc_co_u32_e32 v49, vcc, 0, v37, vcc
	s_mov_b32 s29, 0x23810000
	v_add_co_u32_e32 v50, vcc, s29, v32
	s_nop 0
	v_addc_co_u32_e32 v51, vcc, 0, v33, vcc
	v_readfirstlane_b32 s29, v177
	s_mov_b32 m0, s29
	s_nop 0
	global_load_lds_dwordx4 v[36:37], off
	s_add_i32 m0, s29, 0x8000
	s_nop 0
	global_load_lds_dwordx4 v[38:39], off
	s_add_i32 m0, s29, 0x1000
	s_nop 0
	global_load_lds_dwordx4 v[40:41], off
	s_add_i32 m0, s29, 0x9000
	s_nop 0
	global_load_lds_dwordx4 v[42:43], off
	s_add_i32 m0, s29, 0x2000
	s_nop 0
	global_load_lds_dwordx4 v[44:45], off
	s_add_i32 m0, s29, 0xa000
	s_nop 0
	global_load_lds_dwordx4 v[46:47], off
	s_add_i32 m0, s29, 0x3000
	s_nop 0
	global_load_lds_dwordx4 v[48:49], off
	s_add_i32 m0, s29, 0xb000
	s_nop 0
	global_load_lds_dwordx4 v[50:51], off
	v_lshlrev_b32_e32 v131, 4, v131
	v_and_b32_e32 v131, 0x70, v131
	v_lshl_or_b32 v126, v126, 7, v131
	s_barrier
	s_add_u32 s30, s10, 0xcb20000
	s_addc_u32 s31, s11, 0
	v_lshlrev_b32_e32 v176, 4, v129
	v_or_b32_e32 v129, v130, v176
	v_add_u32_e32 v129, 0x400, v129
	s_add_u32 s16, s16, 0x400
	s_addc_u32 s17, s17, 0
	s_add_u32 s14, s14, 0x100000
	s_addc_u32 s15, s15, 0
	s_cmpk_eq_i32 s16, 0xc00
	s_waitcnt vmcnt(0)
	v_lshlrev_b32_e32 v4, 7, v128
	v_and_b32_e32 v131, 0x2780, v4
	s_waitcnt lgkmcnt(0)
	s_barrier
	s_add_i32 m0, s29, 0x3f80
	s_nop 0
	global_load_lds_dwordx4 v[36:37], off offset:128
	s_add_i32 m0, s29, 0xbf80
	s_nop 0
	global_load_lds_dwordx4 v[38:39], off offset:128
	s_add_i32 m0, s29, 0x4f80
	s_nop 0
	global_load_lds_dwordx4 v[40:41], off offset:128
	s_add_i32 m0, s29, 0xcf80
	s_nop 0
	global_load_lds_dwordx4 v[42:43], off offset:128
	s_add_i32 m0, s29, 0x5f80
	s_nop 0
	global_load_lds_dwordx4 v[44:45], off offset:128
	s_add_i32 m0, s29, 0xdf80
	s_nop 0
	global_load_lds_dwordx4 v[46:47], off offset:128
	s_add_i32 m0, s29, 0x6f80
	s_nop 0
	global_load_lds_dwordx4 v[48:49], off offset:128
	s_add_i32 m0, s29, 0xef80
	s_nop 0
	global_load_lds_dwordx4 v[50:51], off offset:128
	v_lshlrev_b32_e32 v128, 4, v127
	v_or_b32_e32 v127, v130, v128
	v_or_b32_e32 v128, v131, v128
	v_add_u32_e32 v127, 0x400, v127
	v_add_u32_e32 v128, 0x400, v128
	ds_read_b128 v[132:135], v127
	ds_read_b128 v[136:139], v127 offset:2048
	ds_read_b128 v[140:143], v127 offset:4096
	ds_read_b128 v[144:147], v127 offset:6144
	ds_read_b128 v[148:151], v128 offset:32768
	ds_read_b128 v[152:155], v128 offset:34816
	ds_read_b128 v[156:159], v128 offset:36864
	ds_read_b128 v[160:163], v128 offset:38912
	v_or_b32_e32 v130, v131, v176
	v_add_u32_e32 v130, 0x400, v130
	s_waitcnt lgkmcnt(3)
	v_mfma_f32_16x16x32_bf16 v[164:167], v[148:151], v[132:135], 0
	s_waitcnt lgkmcnt(2)
	v_mfma_f32_16x16x32_bf16 v[168:171], v[152:155], v[132:135], 0
	s_waitcnt lgkmcnt(1)
	v_mfma_f32_16x16x32_bf16 v[172:175], v[156:159], v[132:135], 0
	s_waitcnt lgkmcnt(0)
	v_mfma_f32_16x16x32_bf16 v[132:135], v[160:163], v[132:135], 0
	v_mfma_f32_16x16x32_bf16 v[188:191], v[148:151], v[136:139], 0
	v_mfma_f32_16x16x32_bf16 v[192:195], v[152:155], v[136:139], 0
	v_mfma_f32_16x16x32_bf16 v[196:199], v[156:159], v[136:139], 0
	v_mfma_f32_16x16x32_bf16 v[136:139], v[160:163], v[136:139], 0
	v_mfma_f32_16x16x32_bf16 v[200:203], v[148:151], v[140:143], 0
	v_mfma_f32_16x16x32_bf16 v[204:207], v[152:155], v[140:143], 0
	v_mfma_f32_16x16x32_bf16 v[208:211], v[156:159], v[140:143], 0
	v_mfma_f32_16x16x32_bf16 v[140:143], v[160:163], v[140:143], 0
	v_mfma_f32_16x16x32_bf16 v[148:151], v[148:151], v[144:147], 0
	v_mfma_f32_16x16x32_bf16 v[152:155], v[152:155], v[144:147], 0
	v_mfma_f32_16x16x32_bf16 v[156:159], v[156:159], v[144:147], 0
	v_mfma_f32_16x16x32_bf16 v[144:147], v[160:163], v[144:147], 0
	ds_read_b128 v[160:163], v129
	ds_read_b128 v[212:215], v129 offset:2048
	ds_read_b128 v[216:219], v129 offset:4096
	ds_read_b128 v[220:223], v129 offset:6144
	ds_read_b128 v[224:227], v130 offset:32768
	ds_read_b128 v[228:231], v130 offset:34816
	ds_read_b128 v[232:235], v130 offset:36864
	ds_read_b128 v[236:239], v130 offset:38912
	s_waitcnt vmcnt(0)
	s_waitcnt lgkmcnt(0)
	s_barrier
; #define GLOAD(RA, RB, kt_)                                                         \
;   _Pragma("unroll") for (int i = 0; i < 4; ++i) {                                  \
;     RA[i] = *(const u32x4*)(ap + (size_t)(32 * i) * lda + ((kt_) << 6));           \
;     RB[i] = *(const u32x4*)(bp + (size_t)(32 * i) * ldb + ((kt_) << 6));           \
;   }
; #define SWRITE(RA, RB, buf_)                                                       \
;   _Pragma("unroll") for (int i = 0; i < 4; ++i) {                                  \
;     *(u32x4*)(wA + (buf_) * BUF + 32 * i * LDS_STRIDE) = RA[i];                    \
;     *(u32x4*)(wB + (buf_) * BUF + 32 * i * LDS_STRIDE) = RB[i];                    \
;   }
; __device__ __forceinline__ void mma_ktile(const bf16_t* cA, const bf16_t* cB, int fo0, int fo1, f32x4 (&acc)[4][4]) {
; #pragma unroll
;   for (int ks = 0; ks < 2; ++ks) {
;     const int fo = ks ? fo1 : fo0;
;     bf16x8 af[4], bfr[4];
; #pragma unroll
;     for (int i = 0; i < 4; ++i) af[i] = *(const bf16x8*)(cA + i * 16 * LDS_STRIDE + fo);
; #pragma unroll
;     for (int j = 0; j < 4; ++j) bfr[j] = *(const bf16x8*)(cB + j * 16 * LDS_STRIDE + fo);
; #pragma unroll
;     for (int i = 0; i < 4; ++i)
; #pragma unroll
;       for (int j = 0; j < 4; ++j)
;         acc[i][j] = __builtin_amdgcn_mfma_f32_16x16x32_bf16(bfr[j], af[i], acc[i][j], 0, 0, 0);
;   }
; }
; template <bool DEEP>
; __device__ __forceinline__ void gemm_core(const bf16_t* __restrict__ A, int lda, const bf16_t* __restrict__ Bt, int ldb,
;                                           int K, f32x4 (&acc)[4][4], char* smem) {
;     ...
;     for (int kt = 0; kt < nk; ++kt) {
;       const int cur = kt & 1;
;       { const int k1 = min(kt + 1, nk - 1); GLOAD(ra0, rb0, k1); }
;       mma_ktile(cA0 + cur * BUF, cB0 + cur * BUF, fo0, fo1, acc);
;       if (kt + 1 < nk) { SWRITE(ra0, rb0, cur ^ 1); }
;       __syncthreads();
	s_add_i32 m0, s29, 0xffffff00
	s_nop 0
	global_load_lds_dwordx4 v[36:37], off offset:256
	s_add_i32 m0, s29, 0x7f00
	s_nop 0
	global_load_lds_dwordx4 v[38:39], off offset:256
	s_add_i32 m0, s29, 0xf00
	s_nop 0
	global_load_lds_dwordx4 v[40:41], off offset:256
	s_add_i32 m0, s29, 0x8f00
	s_nop 0
	global_load_lds_dwordx4 v[42:43], off offset:256
	s_add_i32 m0, s29, 0x1f00
	s_nop 0
	global_load_lds_dwordx4 v[44:45], off offset:256
	s_add_i32 m0, s29, 0x9f00
	s_nop 0
	global_load_lds_dwordx4 v[46:47], off offset:256
	s_add_i32 m0, s29, 0x2f00
	s_nop 0
	global_load_lds_dwordx4 v[48:49], off offset:256
	s_add_i32 m0, s29, 0xaf00
	s_nop 0
	global_load_lds_dwordx4 v[50:51], off offset:256
	v_mfma_f32_16x16x32_bf16 v[164:167], v[224:227], v[160:163], v[164:167]
	v_mfma_f32_16x16x32_bf16 v[168:171], v[228:231], v[160:163], v[168:171]
	v_mfma_f32_16x16x32_bf16 v[172:175], v[232:235], v[160:163], v[172:175]
	v_mfma_f32_16x16x32_bf16 v[132:135], v[236:239], v[160:163], v[132:135]
	v_mfma_f32_16x16x32_bf16 v[160:163], v[224:227], v[212:215], v[188:191]
	v_mfma_f32_16x16x32_bf16 v[188:191], v[228:231], v[212:215], v[192:195]
	v_mfma_f32_16x16x32_bf16 v[192:195], v[232:235], v[212:215], v[196:199]
	v_mfma_f32_16x16x32_bf16 v[136:139], v[236:239], v[212:215], v[136:139]
	v_mfma_f32_16x16x32_bf16 v[196:199], v[224:227], v[216:219], v[200:203]
	v_mfma_f32_16x16x32_bf16 v[200:203], v[228:231], v[216:219], v[204:207]
	v_mfma_f32_16x16x32_bf16 v[204:207], v[232:235], v[216:219], v[208:211]
	v_mfma_f32_16x16x32_bf16 v[140:143], v[236:239], v[216:219], v[140:143]
	v_mfma_f32_16x16x32_bf16 v[148:151], v[224:227], v[220:223], v[148:151]
	v_mfma_f32_16x16x32_bf16 v[152:155], v[228:231], v[220:223], v[152:155]
	v_mfma_f32_16x16x32_bf16 v[156:159], v[232:235], v[220:223], v[156:159]
	v_mfma_f32_16x16x32_bf16 v[144:147], v[236:239], v[220:223], v[144:147]
	ds_read_b128 v[208:211], v127 offset:16384
	ds_read_b128 v[212:215], v127 offset:18432
	ds_read_b128 v[216:219], v127 offset:20480
	ds_read_b128 v[220:223], v127 offset:22528
	ds_read_b128 v[224:227], v128 offset:49152
	ds_read_b128 v[228:231], v128 offset:51200
	ds_read_b128 v[232:235], v128 offset:53248
	ds_read_b128 v[236:239], v128 offset:55296
	s_waitcnt lgkmcnt(3)
	v_mfma_f32_16x16x32_bf16 v[164:167], v[224:227], v[208:211], v[164:167]
	s_waitcnt lgkmcnt(2)
	v_mfma_f32_16x16x32_bf16 v[168:171], v[228:231], v[208:211], v[168:171]
	s_waitcnt lgkmcnt(1)
	v_mfma_f32_16x16x32_bf16 v[172:175], v[232:235], v[208:211], v[172:175]
	s_waitcnt lgkmcnt(0)
	v_mfma_f32_16x16x32_bf16 v[132:135], v[236:239], v[208:211], v[132:135]
	v_mfma_f32_16x16x32_bf16 v[160:163], v[224:227], v[212:215], v[160:163]
	v_mfma_f32_16x16x32_bf16 v[188:191], v[228:231], v[212:215], v[188:191]
	v_mfma_f32_16x16x32_bf16 v[192:195], v[232:235], v[212:215], v[192:195]
	v_mfma_f32_16x16x32_bf16 v[136:139], v[236:239], v[212:215], v[136:139]
	v_mfma_f32_16x16x32_bf16 v[196:199], v[224:227], v[216:219], v[196:199]
	v_mfma_f32_16x16x32_bf16 v[200:203], v[228:231], v[216:219], v[200:203]
	v_mfma_f32_16x16x32_bf16 v[204:207], v[232:235], v[216:219], v[204:207]
	v_mfma_f32_16x16x32_bf16 v[140:143], v[236:239], v[216:219], v[140:143]
	v_mfma_f32_16x16x32_bf16 v[148:151], v[224:227], v[220:223], v[148:151]
	v_mfma_f32_16x16x32_bf16 v[152:155], v[228:231], v[220:223], v[152:155]
	v_mfma_f32_16x16x32_bf16 v[156:159], v[232:235], v[220:223], v[156:159]
	v_mfma_f32_16x16x32_bf16 v[144:147], v[236:239], v[220:223], v[144:147]
	ds_read_b128 v[208:211], v129 offset:16384
	ds_read_b128 v[212:215], v129 offset:18432
	ds_read_b128 v[216:219], v129 offset:20480
	ds_read_b128 v[220:223], v129 offset:22528
	ds_read_b128 v[224:227], v130 offset:49152
	ds_read_b128 v[228:231], v130 offset:51200
	ds_read_b128 v[232:235], v130 offset:53248
	ds_read_b128 v[236:239], v130 offset:55296
	s_waitcnt vmcnt(0)
	s_waitcnt lgkmcnt(0)
	s_barrier
	s_add_i32 m0, s29, 0x3e80
	s_nop 0
	global_load_lds_dwordx4 v[36:37], off offset:384
	s_add_i32 m0, s29, 0xbe80
	s_nop 0
	global_load_lds_dwordx4 v[38:39], off offset:384
	s_add_i32 m0, s29, 0x4e80
	s_nop 0
	global_load_lds_dwordx4 v[40:41], off offset:384
	s_add_i32 m0, s29, 0xce80
	s_nop 0
	global_load_lds_dwordx4 v[42:43], off offset:384
	s_add_i32 m0, s29, 0x5e80
	s_nop 0
	global_load_lds_dwordx4 v[44:45], off offset:384
	s_add_i32 m0, s29, 0xde80
	s_nop 0
	global_load_lds_dwordx4 v[46:47], off offset:384
	s_add_i32 m0, s29, 0x6e80
	s_nop 0
	global_load_lds_dwordx4 v[48:49], off offset:384
	s_add_i32 m0, s29, 0xee80
	s_nop 0
	global_load_lds_dwordx4 v[50:51], off offset:384
	v_mfma_f32_16x16x32_bf16 v[164:167], v[224:227], v[208:211], v[164:167]
	v_mfma_f32_16x16x32_bf16 v[168:171], v[228:231], v[208:211], v[168:171]
	v_mfma_f32_16x16x32_bf16 v[172:175], v[232:235], v[208:211], v[172:175]
	v_mfma_f32_16x16x32_bf16 v[132:135], v[236:239], v[208:211], v[132:135]
	v_mfma_f32_16x16x32_bf16 v[160:163], v[224:227], v[212:215], v[160:163]
	v_mfma_f32_16x16x32_bf16 v[188:191], v[228:231], v[212:215], v[188:191]
	v_mfma_f32_16x16x32_bf16 v[192:195], v[232:235], v[212:215], v[192:195]
	v_mfma_f32_16x16x32_bf16 v[136:139], v[236:239], v[212:215], v[136:139]
	v_mfma_f32_16x16x32_bf16 v[196:199], v[224:227], v[216:219], v[196:199]
	v_mfma_f32_16x16x32_bf16 v[200:203], v[228:231], v[216:219], v[200:203]
	v_mfma_f32_16x16x32_bf16 v[204:207], v[232:235], v[216:219], v[204:207]
	v_mfma_f32_16x16x32_bf16 v[140:143], v[236:239], v[216:219], v[140:143]
	v_mfma_f32_16x16x32_bf16 v[148:151], v[224:227], v[220:223], v[148:151]
	v_mfma_f32_16x16x32_bf16 v[152:155], v[228:231], v[220:223], v[152:155]
	v_mfma_f32_16x16x32_bf16 v[156:159], v[232:235], v[220:223], v[156:159]
	v_mfma_f32_16x16x32_bf16 v[144:147], v[236:239], v[220:223], v[144:147]
	ds_read_b128 v[208:211], v127
	ds_read_b128 v[212:215], v127 offset:2048
	ds_read_b128 v[216:219], v127 offset:4096
	ds_read_b128 v[220:223], v127 offset:6144
	ds_read_b128 v[224:227], v128 offset:32768
	ds_read_b128 v[228:231], v128 offset:34816
	ds_read_b128 v[232:235], v128 offset:36864
	ds_read_b128 v[236:239], v128 offset:38912
	s_waitcnt lgkmcnt(3)
; #define GLOAD(RA, RB, kt_)                                                         \
;   _Pragma("unroll") for (int i = 0; i < 4; ++i) {                                  \
;     RA[i] = *(const u32x4*)(ap + (size_t)(32 * i) * lda + ((kt_) << 6));           \
;     RB[i] = *(const u32x4*)(bp + (size_t)(32 * i) * ldb + ((kt_) << 6));           \
;   }
; #define SWRITE(RA, RB, buf_)                                                       \
;   _Pragma("unroll") for (int i = 0; i < 4; ++i) {                                  \
;     *(u32x4*)(wA + (buf_) * BUF + 32 * i * LDS_STRIDE) = RA[i];                    \
;     *(u32x4*)(wB + (buf_) * BUF + 32 * i * LDS_STRIDE) = RB[i];                    \
;   }
; __device__ __forceinline__ void mma_ktile(const bf16_t* cA, const bf16_t* cB, int fo0, int fo1, f32x4 (&acc)[4][4]) {
; #pragma unroll
;   for (int ks = 0; ks < 2; ++ks) {
;     const int fo = ks ? fo1 : fo0;
;     bf16x8 af[4], bfr[4];
; #pragma unroll
;     for (int i = 0; i < 4; ++i) af[i] = *(const bf16x8*)(cA + i * 16 * LDS_STRIDE + fo);
; #pragma unroll
;     for (int j = 0; j < 4; ++j) bfr[j] = *(const bf16x8*)(cB + j * 16 * LDS_STRIDE + fo);
; #pragma unroll
;     for (int i = 0; i < 4; ++i)
; #pragma unroll
;       for (int j = 0; j < 4; ++j)
;         acc[i][j] = __builtin_amdgcn_mfma_f32_16x16x32_bf16(bfr[j], af[i], acc[i][j], 0, 0, 0);
;   }
; }
; template <bool DEEP>
; __device__ __forceinline__ void gemm_core(const bf16_t* __restrict__ A, int lda, const bf16_t* __restrict__ Bt, int ldb,
;                                           int K, f32x4 (&acc)[4][4], char* smem) {
;     ...
;     for (int kt = 0; kt < nk; ++kt) {
;       const int cur = kt & 1;
;       { const int k1 = min(kt + 1, nk - 1); GLOAD(ra0, rb0, k1); }
;       mma_ktile(cA0 + cur * BUF, cB0 + cur * BUF, fo0, fo1, acc);
;       if (kt + 1 < nk) { SWRITE(ra0, rb0, cur ^ 1); }
;       __syncthreads();
	v_mfma_f32_16x16x32_bf16 v[164:167], v[224:227], v[208:211], v[164:167]
	s_waitcnt lgkmcnt(2)
	v_mfma_f32_16x16x32_bf16 v[168:171], v[228:231], v[208:211], v[168:171]
	s_waitcnt lgkmcnt(1)
	v_mfma_f32_16x16x32_bf16 v[172:175], v[232:235], v[208:211], v[172:175]
	s_waitcnt lgkmcnt(0)
	v_mfma_f32_16x16x32_bf16 v[132:135], v[236:239], v[208:211], v[132:135]
	v_mfma_f32_16x16x32_bf16 v[160:163], v[224:227], v[212:215], v[160:163]
	v_mfma_f32_16x16x32_bf16 v[188:191], v[228:231], v[212:215], v[188:191]
	v_mfma_f32_16x16x32_bf16 v[192:195], v[232:235], v[212:215], v[192:195]
	v_mfma_f32_16x16x32_bf16 v[136:139], v[236:239], v[212:215], v[136:139]
	v_mfma_f32_16x16x32_bf16 v[196:199], v[224:227], v[216:219], v[196:199]
	v_mfma_f32_16x16x32_bf16 v[200:203], v[228:231], v[216:219], v[200:203]
	v_mfma_f32_16x16x32_bf16 v[204:207], v[232:235], v[216:219], v[204:207]
	v_mfma_f32_16x16x32_bf16 v[140:143], v[236:239], v[216:219], v[140:143]
	v_mfma_f32_16x16x32_bf16 v[148:151], v[224:227], v[220:223], v[148:151]
	v_mfma_f32_16x16x32_bf16 v[152:155], v[228:231], v[220:223], v[152:155]
	v_mfma_f32_16x16x32_bf16 v[156:159], v[232:235], v[220:223], v[156:159]
	v_mfma_f32_16x16x32_bf16 v[144:147], v[236:239], v[220:223], v[144:147]
	ds_read_b128 v[208:211], v129
	ds_read_b128 v[212:215], v129 offset:2048
	ds_read_b128 v[216:219], v129 offset:4096
	ds_read_b128 v[220:223], v129 offset:6144
	ds_read_b128 v[224:227], v130 offset:32768
	ds_read_b128 v[228:231], v130 offset:34816
	ds_read_b128 v[232:235], v130 offset:36864
	ds_read_b128 v[236:239], v130 offset:38912
	s_waitcnt vmcnt(0)
	s_waitcnt lgkmcnt(0)
	s_barrier
	s_add_i32 m0, s29, 0xfffffe00
	s_nop 0
	global_load_lds_dwordx4 v[36:37], off offset:512
	s_add_i32 m0, s29, 0x7e00
	s_nop 0
	global_load_lds_dwordx4 v[38:39], off offset:512
	s_add_i32 m0, s29, 0xe00
	s_nop 0
	global_load_lds_dwordx4 v[40:41], off offset:512
	s_add_i32 m0, s29, 0x8e00
	s_nop 0
	global_load_lds_dwordx4 v[42:43], off offset:512
	s_add_i32 m0, s29, 0x1e00
	s_nop 0
	global_load_lds_dwordx4 v[44:45], off offset:512
	s_add_i32 m0, s29, 0x9e00
	s_nop 0
	global_load_lds_dwordx4 v[46:47], off offset:512
	s_add_i32 m0, s29, 0x2e00
	s_nop 0
	global_load_lds_dwordx4 v[48:49], off offset:512
	s_add_i32 m0, s29, 0xae00
	s_nop 0
	global_load_lds_dwordx4 v[50:51], off offset:512
	v_mfma_f32_16x16x32_bf16 v[164:167], v[224:227], v[208:211], v[164:167]
	v_mfma_f32_16x16x32_bf16 v[168:171], v[228:231], v[208:211], v[168:171]
	v_mfma_f32_16x16x32_bf16 v[172:175], v[232:235], v[208:211], v[172:175]
	v_mfma_f32_16x16x32_bf16 v[132:135], v[236:239], v[208:211], v[132:135]
	v_mfma_f32_16x16x32_bf16 v[160:163], v[224:227], v[212:215], v[160:163]
	v_mfma_f32_16x16x32_bf16 v[188:191], v[228:231], v[212:215], v[188:191]
	v_mfma_f32_16x16x32_bf16 v[192:195], v[232:235], v[212:215], v[192:195]
	v_mfma_f32_16x16x32_bf16 v[136:139], v[236:239], v[212:215], v[136:139]
	v_mfma_f32_16x16x32_bf16 v[196:199], v[224:227], v[216:219], v[196:199]
	v_mfma_f32_16x16x32_bf16 v[200:203], v[228:231], v[216:219], v[200:203]
	v_mfma_f32_16x16x32_bf16 v[204:207], v[232:235], v[216:219], v[204:207]
	v_mfma_f32_16x16x32_bf16 v[140:143], v[236:239], v[216:219], v[140:143]
	v_mfma_f32_16x16x32_bf16 v[148:151], v[224:227], v[220:223], v[148:151]
	v_mfma_f32_16x16x32_bf16 v[152:155], v[228:231], v[220:223], v[152:155]
	v_mfma_f32_16x16x32_bf16 v[156:159], v[232:235], v[220:223], v[156:159]
	v_mfma_f32_16x16x32_bf16 v[144:147], v[236:239], v[220:223], v[144:147]
	ds_read_b128 v[208:211], v127 offset:16384
	ds_read_b128 v[212:215], v127 offset:18432
	ds_read_b128 v[216:219], v127 offset:20480
	ds_read_b128 v[220:223], v127 offset:22528
	ds_read_b128 v[224:227], v128 offset:49152
	ds_read_b128 v[228:231], v128 offset:51200
	ds_read_b128 v[232:235], v128 offset:53248
	ds_read_b128 v[236:239], v128 offset:55296
	s_waitcnt lgkmcnt(3)
	v_mfma_f32_16x16x32_bf16 v[164:167], v[224:227], v[208:211], v[164:167]
	s_waitcnt lgkmcnt(2)
	v_mfma_f32_16x16x32_bf16 v[168:171], v[228:231], v[208:211], v[168:171]
	s_waitcnt lgkmcnt(1)
	v_mfma_f32_16x16x32_bf16 v[172:175], v[232:235], v[208:211], v[172:175]
	s_waitcnt lgkmcnt(0)
	v_mfma_f32_16x16x32_bf16 v[132:135], v[236:239], v[208:211], v[132:135]
	v_mfma_f32_16x16x32_bf16 v[160:163], v[224:227], v[212:215], v[160:163]
	v_mfma_f32_16x16x32_bf16 v[188:191], v[228:231], v[212:215], v[188:191]
	v_mfma_f32_16x16x32_bf16 v[192:195], v[232:235], v[212:215], v[192:195]
	v_mfma_f32_16x16x32_bf16 v[136:139], v[236:239], v[212:215], v[136:139]
	v_mfma_f32_16x16x32_bf16 v[196:199], v[224:227], v[216:219], v[196:199]
	v_mfma_f32_16x16x32_bf16 v[200:203], v[228:231], v[216:219], v[200:203]
	v_mfma_f32_16x16x32_bf16 v[204:207], v[232:235], v[216:219], v[204:207]
	v_mfma_f32_16x16x32_bf16 v[140:143], v[236:239], v[216:219], v[140:143]
	v_mfma_f32_16x16x32_bf16 v[148:151], v[224:227], v[220:223], v[148:151]
	v_mfma_f32_16x16x32_bf16 v[152:155], v[228:231], v[220:223], v[152:155]
	v_mfma_f32_16x16x32_bf16 v[156:159], v[232:235], v[220:223], v[156:159]
	v_mfma_f32_16x16x32_bf16 v[144:147], v[236:239], v[220:223], v[144:147]
	ds_read_b128 v[208:211], v129 offset:16384
	ds_read_b128 v[212:215], v129 offset:18432
	ds_read_b128 v[216:219], v129 offset:20480
	ds_read_b128 v[220:223], v129 offset:22528
	ds_read_b128 v[224:227], v130 offset:49152
	ds_read_b128 v[228:231], v130 offset:51200
	ds_read_b128 v[232:235], v130 offset:53248
	ds_read_b128 v[236:239], v130 offset:55296
	s_waitcnt vmcnt(0)
	s_waitcnt lgkmcnt(0)
	s_barrier
; #define GLOAD(RA, RB, kt_)                                                         \
;   _Pragma("unroll") for (int i = 0; i < 4; ++i) {                                  \
;     RA[i] = *(const u32x4*)(ap + (size_t)(32 * i) * lda + ((kt_) << 6));           \
;     RB[i] = *(const u32x4*)(bp + (size_t)(32 * i) * ldb + ((kt_) << 6));           \
;   }
; #define SWRITE(RA, RB, buf_)                                                       \
;   _Pragma("unroll") for (int i = 0; i < 4; ++i) {                                  \
;     *(u32x4*)(wA + (buf_) * BUF + 32 * i * LDS_STRIDE) = RA[i];                    \
;     *(u32x4*)(wB + (buf_) * BUF + 32 * i * LDS_STRIDE) = RB[i];                    \
;   }
; __device__ __forceinline__ void mma_ktile(const bf16_t* cA, const bf16_t* cB, int fo0, int fo1, f32x4 (&acc)[4][4]) {
; #pragma unroll
;   for (int ks = 0; ks < 2; ++ks) {
;     const int fo = ks ? fo1 : fo0;
;     bf16x8 af[4], bfr[4];
; #pragma unroll
;     for (int i = 0; i < 4; ++i) af[i] = *(const bf16x8*)(cA + i * 16 * LDS_STRIDE + fo);
; #pragma unroll
;     for (int j = 0; j < 4; ++j) bfr[j] = *(const bf16x8*)(cB + j * 16 * LDS_STRIDE + fo);
; #pragma unroll
;     for (int i = 0; i < 4; ++i)
; #pragma unroll
;       for (int j = 0; j < 4; ++j)
;         acc[i][j] = __builtin_amdgcn_mfma_f32_16x16x32_bf16(bfr[j], af[i], acc[i][j], 0, 0, 0);
;   }
; }
; template <bool DEEP>
; __device__ __forceinline__ void gemm_core(const bf16_t* __restrict__ A, int lda, const bf16_t* __restrict__ Bt, int ldb,
;                                           int K, f32x4 (&acc)[4][4], char* smem) {
;     ...
;     for (int kt = 0; kt < nk; ++kt) {
;       const int cur = kt & 1;
;       { const int k1 = min(kt + 1, nk - 1); GLOAD(ra0, rb0, k1); }
;       mma_ktile(cA0 + cur * BUF, cB0 + cur * BUF, fo0, fo1, acc);
;       if (kt + 1 < nk) { SWRITE(ra0, rb0, cur ^ 1); }
;       __syncthreads();
	s_add_i32 m0, s29, 0x3d80
	s_nop 0
	global_load_lds_dwordx4 v[36:37], off offset:640
	s_add_i32 m0, s29, 0xbd80
	s_nop 0
	global_load_lds_dwordx4 v[38:39], off offset:640
	s_add_i32 m0, s29, 0x4d80
	s_nop 0
	global_load_lds_dwordx4 v[40:41], off offset:640
	s_add_i32 m0, s29, 0xcd80
	s_nop 0
	global_load_lds_dwordx4 v[42:43], off offset:640
	s_add_i32 m0, s29, 0x5d80
	s_nop 0
	global_load_lds_dwordx4 v[44:45], off offset:640
	s_add_i32 m0, s29, 0xdd80
	s_nop 0
	global_load_lds_dwordx4 v[46:47], off offset:640
	s_add_i32 m0, s29, 0x6d80
	s_nop 0
	global_load_lds_dwordx4 v[48:49], off offset:640
	s_add_i32 m0, s29, 0xed80
	s_nop 0
	global_load_lds_dwordx4 v[50:51], off offset:640
	v_mfma_f32_16x16x32_bf16 v[164:167], v[224:227], v[208:211], v[164:167]
	v_mfma_f32_16x16x32_bf16 v[168:171], v[228:231], v[208:211], v[168:171]
	v_mfma_f32_16x16x32_bf16 v[172:175], v[232:235], v[208:211], v[172:175]
	v_mfma_f32_16x16x32_bf16 v[132:135], v[236:239], v[208:211], v[132:135]
	v_mfma_f32_16x16x32_bf16 v[160:163], v[224:227], v[212:215], v[160:163]
	v_mfma_f32_16x16x32_bf16 v[188:191], v[228:231], v[212:215], v[188:191]
	v_mfma_f32_16x16x32_bf16 v[192:195], v[232:235], v[212:215], v[192:195]
	v_mfma_f32_16x16x32_bf16 v[136:139], v[236:239], v[212:215], v[136:139]
	v_mfma_f32_16x16x32_bf16 v[196:199], v[224:227], v[216:219], v[196:199]
	v_mfma_f32_16x16x32_bf16 v[200:203], v[228:231], v[216:219], v[200:203]
	v_mfma_f32_16x16x32_bf16 v[204:207], v[232:235], v[216:219], v[204:207]
	v_mfma_f32_16x16x32_bf16 v[140:143], v[236:239], v[216:219], v[140:143]
	v_mfma_f32_16x16x32_bf16 v[148:151], v[224:227], v[220:223], v[148:151]
	v_mfma_f32_16x16x32_bf16 v[152:155], v[228:231], v[220:223], v[152:155]
	v_mfma_f32_16x16x32_bf16 v[156:159], v[232:235], v[220:223], v[156:159]
	v_mfma_f32_16x16x32_bf16 v[144:147], v[236:239], v[220:223], v[144:147]
	ds_read_b128 v[208:211], v127
	ds_read_b128 v[212:215], v127 offset:2048
	ds_read_b128 v[216:219], v127 offset:4096
	ds_read_b128 v[220:223], v127 offset:6144
	ds_read_b128 v[224:227], v128 offset:32768
	ds_read_b128 v[228:231], v128 offset:34816
	ds_read_b128 v[232:235], v128 offset:36864
	ds_read_b128 v[236:239], v128 offset:38912
	s_waitcnt lgkmcnt(3)
	v_mfma_f32_16x16x32_bf16 v[164:167], v[224:227], v[208:211], v[164:167]
	s_waitcnt lgkmcnt(2)
	v_mfma_f32_16x16x32_bf16 v[168:171], v[228:231], v[208:211], v[168:171]
	s_waitcnt lgkmcnt(1)
	v_mfma_f32_16x16x32_bf16 v[172:175], v[232:235], v[208:211], v[172:175]
	s_waitcnt lgkmcnt(0)
	v_mfma_f32_16x16x32_bf16 v[132:135], v[236:239], v[208:211], v[132:135]
	v_mfma_f32_16x16x32_bf16 v[160:163], v[224:227], v[212:215], v[160:163]
	v_mfma_f32_16x16x32_bf16 v[188:191], v[228:231], v[212:215], v[188:191]
	v_mfma_f32_16x16x32_bf16 v[192:195], v[232:235], v[212:215], v[192:195]
	v_mfma_f32_16x16x32_bf16 v[136:139], v[236:239], v[212:215], v[136:139]
	v_mfma_f32_16x16x32_bf16 v[196:199], v[224:227], v[216:219], v[196:199]
	v_mfma_f32_16x16x32_bf16 v[200:203], v[228:231], v[216:219], v[200:203]
	v_mfma_f32_16x16x32_bf16 v[204:207], v[232:235], v[216:219], v[204:207]
	v_mfma_f32_16x16x32_bf16 v[140:143], v[236:239], v[216:219], v[140:143]
	v_mfma_f32_16x16x32_bf16 v[148:151], v[224:227], v[220:223], v[148:151]
	v_mfma_f32_16x16x32_bf16 v[152:155], v[228:231], v[220:223], v[152:155]
	v_mfma_f32_16x16x32_bf16 v[156:159], v[232:235], v[220:223], v[156:159]
	v_mfma_f32_16x16x32_bf16 v[144:147], v[236:239], v[220:223], v[144:147]
	ds_read_b128 v[208:211], v129
	ds_read_b128 v[212:215], v129 offset:2048
	ds_read_b128 v[216:219], v129 offset:4096
	ds_read_b128 v[220:223], v129 offset:6144
	ds_read_b128 v[224:227], v130 offset:32768
	ds_read_b128 v[228:231], v130 offset:34816
	ds_read_b128 v[232:235], v130 offset:36864
	ds_read_b128 v[236:239], v130 offset:38912
	s_waitcnt vmcnt(0)
	s_waitcnt lgkmcnt(0)
	s_barrier
	s_add_i32 m0, s29, 0xfffffd00
	s_nop 0
	global_load_lds_dwordx4 v[36:37], off offset:768
	s_add_i32 m0, s29, 0x7d00
	s_nop 0
	global_load_lds_dwordx4 v[38:39], off offset:768
	s_add_i32 m0, s29, 0xd00
	s_nop 0
	global_load_lds_dwordx4 v[40:41], off offset:768
	s_add_i32 m0, s29, 0x8d00
	s_nop 0
	global_load_lds_dwordx4 v[42:43], off offset:768
	s_add_i32 m0, s29, 0x1d00
	s_nop 0
	global_load_lds_dwordx4 v[44:45], off offset:768
	s_add_i32 m0, s29, 0x9d00
	s_nop 0
	global_load_lds_dwordx4 v[46:47], off offset:768
	s_add_i32 m0, s29, 0x2d00
	s_nop 0
	global_load_lds_dwordx4 v[48:49], off offset:768
	s_add_i32 m0, s29, 0xad00
	s_nop 0
	global_load_lds_dwordx4 v[50:51], off offset:768
	v_mfma_f32_16x16x32_bf16 v[164:167], v[224:227], v[208:211], v[164:167]
	v_mfma_f32_16x16x32_bf16 v[168:171], v[228:231], v[208:211], v[168:171]
	v_mfma_f32_16x16x32_bf16 v[172:175], v[232:235], v[208:211], v[172:175]
	v_mfma_f32_16x16x32_bf16 v[132:135], v[236:239], v[208:211], v[132:135]
	v_mfma_f32_16x16x32_bf16 v[160:163], v[224:227], v[212:215], v[160:163]
	v_mfma_f32_16x16x32_bf16 v[188:191], v[228:231], v[212:215], v[188:191]
	v_mfma_f32_16x16x32_bf16 v[192:195], v[232:235], v[212:215], v[192:195]
	v_mfma_f32_16x16x32_bf16 v[136:139], v[236:239], v[212:215], v[136:139]
	v_mfma_f32_16x16x32_bf16 v[196:199], v[224:227], v[216:219], v[196:199]
	v_mfma_f32_16x16x32_bf16 v[200:203], v[228:231], v[216:219], v[200:203]
	v_mfma_f32_16x16x32_bf16 v[204:207], v[232:235], v[216:219], v[204:207]
	v_mfma_f32_16x16x32_bf16 v[140:143], v[236:239], v[216:219], v[140:143]
	v_mfma_f32_16x16x32_bf16 v[148:151], v[224:227], v[220:223], v[148:151]
	v_mfma_f32_16x16x32_bf16 v[152:155], v[228:231], v[220:223], v[152:155]
	v_mfma_f32_16x16x32_bf16 v[156:159], v[232:235], v[220:223], v[156:159]
	v_mfma_f32_16x16x32_bf16 v[144:147], v[236:239], v[220:223], v[144:147]
	ds_read_b128 v[208:211], v127 offset:16384
	ds_read_b128 v[212:215], v127 offset:18432
	ds_read_b128 v[216:219], v127 offset:20480
	ds_read_b128 v[220:223], v127 offset:22528
	ds_read_b128 v[224:227], v128 offset:49152
	ds_read_b128 v[228:231], v128 offset:51200
	ds_read_b128 v[232:235], v128 offset:53248
	ds_read_b128 v[236:239], v128 offset:55296
	s_waitcnt lgkmcnt(3)
; #define GLOAD(RA, RB, kt_)                                                         \
;   _Pragma("unroll") for (int i = 0; i < 4; ++i) {                                  \
;     RA[i] = *(const u32x4*)(ap + (size_t)(32 * i) * lda + ((kt_) << 6));           \
;     RB[i] = *(const u32x4*)(bp + (size_t)(32 * i) * ldb + ((kt_) << 6));           \
;   }
; #define SWRITE(RA, RB, buf_)                                                       \
;   _Pragma("unroll") for (int i = 0; i < 4; ++i) {                                  \
;     *(u32x4*)(wA + (buf_) * BUF + 32 * i * LDS_STRIDE) = RA[i];                    \
;     *(u32x4*)(wB + (buf_) * BUF + 32 * i * LDS_STRIDE) = RB[i];                    \
;   }
; __device__ __forceinline__ void mma_ktile(const bf16_t* cA, const bf16_t* cB, int fo0, int fo1, f32x4 (&acc)[4][4]) {
; #pragma unroll
;   for (int ks = 0; ks < 2; ++ks) {
;     const int fo = ks ? fo1 : fo0;
;     bf16x8 af[4], bfr[4];
; #pragma unroll
;     for (int i = 0; i < 4; ++i) af[i] = *(const bf16x8*)(cA + i * 16 * LDS_STRIDE + fo);
; #pragma unroll
;     for (int j = 0; j < 4; ++j) bfr[j] = *(const bf16x8*)(cB + j * 16 * LDS_STRIDE + fo);
; #pragma unroll
;     for (int i = 0; i < 4; ++i)
; #pragma unroll
;       for (int j = 0; j < 4; ++j)
;         acc[i][j] = __builtin_amdgcn_mfma_f32_16x16x32_bf16(bfr[j], af[i], acc[i][j], 0, 0, 0);
;   }
; }
; template <bool DEEP>
; __device__ __forceinline__ void gemm_core(const bf16_t* __restrict__ A, int lda, const bf16_t* __restrict__ Bt, int ldb,
;                                           int K, f32x4 (&acc)[4][4], char* smem) {
;     ...
;     for (int kt = 0; kt < nk; ++kt) {
;       const int cur = kt & 1;
;       { const int k1 = min(kt + 1, nk - 1); GLOAD(ra0, rb0, k1); }
;       mma_ktile(cA0 + cur * BUF, cB0 + cur * BUF, fo0, fo1, acc);
;       if (kt + 1 < nk) { SWRITE(ra0, rb0, cur ^ 1); }
;       __syncthreads();
	v_mfma_f32_16x16x32_bf16 v[164:167], v[224:227], v[208:211], v[164:167]
	s_waitcnt lgkmcnt(2)
	v_mfma_f32_16x16x32_bf16 v[168:171], v[228:231], v[208:211], v[168:171]
	s_waitcnt lgkmcnt(1)
	v_mfma_f32_16x16x32_bf16 v[172:175], v[232:235], v[208:211], v[172:175]
	s_waitcnt lgkmcnt(0)
	v_mfma_f32_16x16x32_bf16 v[132:135], v[236:239], v[208:211], v[132:135]
	v_mfma_f32_16x16x32_bf16 v[160:163], v[224:227], v[212:215], v[160:163]
	v_mfma_f32_16x16x32_bf16 v[188:191], v[228:231], v[212:215], v[188:191]
	v_mfma_f32_16x16x32_bf16 v[192:195], v[232:235], v[212:215], v[192:195]
	v_mfma_f32_16x16x32_bf16 v[136:139], v[236:239], v[212:215], v[136:139]
	v_mfma_f32_16x16x32_bf16 v[196:199], v[224:227], v[216:219], v[196:199]
	v_mfma_f32_16x16x32_bf16 v[200:203], v[228:231], v[216:219], v[200:203]
	v_mfma_f32_16x16x32_bf16 v[204:207], v[232:235], v[216:219], v[204:207]
	v_mfma_f32_16x16x32_bf16 v[140:143], v[236:239], v[216:219], v[140:143]
	v_mfma_f32_16x16x32_bf16 v[148:151], v[224:227], v[220:223], v[148:151]
	v_mfma_f32_16x16x32_bf16 v[152:155], v[228:231], v[220:223], v[152:155]
	v_mfma_f32_16x16x32_bf16 v[156:159], v[232:235], v[220:223], v[156:159]
	v_mfma_f32_16x16x32_bf16 v[144:147], v[236:239], v[220:223], v[144:147]
	ds_read_b128 v[208:211], v129 offset:16384
	ds_read_b128 v[212:215], v129 offset:18432
	ds_read_b128 v[216:219], v129 offset:20480
	ds_read_b128 v[220:223], v129 offset:22528
	ds_read_b128 v[224:227], v130 offset:49152
	ds_read_b128 v[228:231], v130 offset:51200
	ds_read_b128 v[232:235], v130 offset:53248
	ds_read_b128 v[236:239], v130 offset:55296
	s_waitcnt vmcnt(0)
	s_waitcnt lgkmcnt(0)
	s_barrier
	s_add_i32 m0, s29, 0x3c80
	s_nop 0
	global_load_lds_dwordx4 v[36:37], off offset:896
	s_add_i32 m0, s29, 0xbc80
	s_nop 0
	global_load_lds_dwordx4 v[38:39], off offset:896
	s_add_i32 m0, s29, 0x4c80
	s_nop 0
	global_load_lds_dwordx4 v[40:41], off offset:896
	s_add_i32 m0, s29, 0xcc80
	s_nop 0
	global_load_lds_dwordx4 v[42:43], off offset:896
	s_add_i32 m0, s29, 0x5c80
	s_nop 0
	global_load_lds_dwordx4 v[44:45], off offset:896
	s_add_i32 m0, s29, 0xdc80
	s_nop 0
	global_load_lds_dwordx4 v[46:47], off offset:896
	s_add_i32 m0, s29, 0x6c80
	s_nop 0
	global_load_lds_dwordx4 v[48:49], off offset:896
	s_add_i32 m0, s29, 0xec80
	s_nop 0
	global_load_lds_dwordx4 v[50:51], off offset:896
	v_mfma_f32_16x16x32_bf16 v[164:167], v[224:227], v[208:211], v[164:167]
	v_mfma_f32_16x16x32_bf16 v[168:171], v[228:231], v[208:211], v[168:171]
	v_mfma_f32_16x16x32_bf16 v[172:175], v[232:235], v[208:211], v[172:175]
	v_mfma_f32_16x16x32_bf16 v[132:135], v[236:239], v[208:211], v[132:135]
	v_mfma_f32_16x16x32_bf16 v[160:163], v[224:227], v[212:215], v[160:163]
	v_mfma_f32_16x16x32_bf16 v[188:191], v[228:231], v[212:215], v[188:191]
	v_mfma_f32_16x16x32_bf16 v[192:195], v[232:235], v[212:215], v[192:195]
	v_mfma_f32_16x16x32_bf16 v[136:139], v[236:239], v[212:215], v[136:139]
	v_mfma_f32_16x16x32_bf16 v[196:199], v[224:227], v[216:219], v[196:199]
	v_mfma_f32_16x16x32_bf16 v[200:203], v[228:231], v[216:219], v[200:203]
	v_mfma_f32_16x16x32_bf16 v[204:207], v[232:235], v[216:219], v[204:207]
	v_mfma_f32_16x16x32_bf16 v[140:143], v[236:239], v[216:219], v[140:143]
	v_mfma_f32_16x16x32_bf16 v[148:151], v[224:227], v[220:223], v[148:151]
	v_mfma_f32_16x16x32_bf16 v[152:155], v[228:231], v[220:223], v[152:155]
	v_mfma_f32_16x16x32_bf16 v[156:159], v[232:235], v[220:223], v[156:159]
	v_mfma_f32_16x16x32_bf16 v[144:147], v[236:239], v[220:223], v[144:147]
	global_load_dwordx2 v[224:225], v110, s[30:31] offset:3072
	global_load_dwordx2 v[226:227], v110, s[30:31] offset:3104
	global_load_dwordx2 v[228:229], v110, s[30:31] offset:3136
	global_load_dwordx2 v[230:231], v110, s[30:31] offset:3168
	global_load_dwordx2 v[232:233], v106, s[30:31] offset:3072
	global_load_dwordx2 v[234:235], v106, s[30:31] offset:3104
	global_load_dwordx2 v[236:237], v106, s[30:31] offset:3136
	global_load_dwordx2 v[238:239], v106, s[30:31] offset:3168
	ds_read_b128 v[36:39], v127
	ds_read_b128 v[40:43], v127 offset:2048
	ds_read_b128 v[44:47], v127 offset:4096
	ds_read_b128 v[48:51], v127 offset:6144
	ds_read_b128 v[208:211], v128 offset:32768
	ds_read_b128 v[212:215], v128 offset:34816
	ds_read_b128 v[216:219], v128 offset:36864
	ds_read_b128 v[220:223], v128 offset:38912
	s_waitcnt lgkmcnt(3)
	v_mfma_f32_16x16x32_bf16 v[164:167], v[208:211], v[36:39], v[164:167]
	s_waitcnt lgkmcnt(2)
	v_mfma_f32_16x16x32_bf16 v[168:171], v[212:215], v[36:39], v[168:171]
	s_waitcnt lgkmcnt(1)
	v_mfma_f32_16x16x32_bf16 v[172:175], v[216:219], v[36:39], v[172:175]
	s_waitcnt lgkmcnt(0)
	v_mfma_f32_16x16x32_bf16 v[36:39], v[220:223], v[36:39], v[132:135]
	v_mfma_f32_16x16x32_bf16 v[132:135], v[208:211], v[40:43], v[160:163]
	v_mfma_f32_16x16x32_bf16 v[160:163], v[212:215], v[40:43], v[188:191]
	v_mfma_f32_16x16x32_bf16 v[188:191], v[216:219], v[40:43], v[192:195]
	v_mfma_f32_16x16x32_bf16 v[40:43], v[220:223], v[40:43], v[136:139]
	v_mfma_f32_16x16x32_bf16 v[136:139], v[208:211], v[44:47], v[196:199]
	v_mfma_f32_16x16x32_bf16 v[192:195], v[212:215], v[44:47], v[200:203]
	v_mfma_f32_16x16x32_bf16 v[196:199], v[216:219], v[44:47], v[204:207]
	v_mfma_f32_16x16x32_bf16 v[44:47], v[220:223], v[44:47], v[140:143]
	v_mfma_f32_16x16x32_bf16 v[140:143], v[208:211], v[48:51], v[148:151]
	v_mfma_f32_16x16x32_bf16 v[148:151], v[212:215], v[48:51], v[152:155]
	v_mfma_f32_16x16x32_bf16 v[152:155], v[216:219], v[48:51], v[156:159]
	v_mfma_f32_16x16x32_bf16 v[48:51], v[220:223], v[48:51], v[144:147]
	s_nop 2
	ds_read_b128 v[144:147], v129
	ds_read_b128 v[156:159], v129 offset:2048
	ds_read_b128 v[200:203], v129 offset:4096
	ds_read_b128 v[204:207], v129 offset:6144
	ds_read_b128 v[208:211], v130 offset:32768
	ds_read_b128 v[212:215], v130 offset:34816
	ds_read_b128 v[216:219], v130 offset:36864
	ds_read_b128 v[220:223], v130 offset:38912
	s_waitcnt vmcnt(8)
	s_waitcnt lgkmcnt(0)
	s_barrier
; __device__ __forceinline__ float bflo(unsigned u) { return __uint_as_float(u << 16); }
; __device__ __forceinline__ float bfhi(unsigned u) { return __uint_as_float(u & 0xffff0000u); }
; __device__ __forceinline__ float sigmoidf_(float x) { return frcp_(1.f + __expf(-x)); }
; __device__ __forceinline__ void mma_ktile(const bf16_t* cA, const bf16_t* cB, int fo0, int fo1, f32x4 (&acc)[4][4]) {
; #pragma unroll
;   for (int ks = 0; ks < 2; ++ks) {
;     const int fo = ks ? fo1 : fo0;
;     bf16x8 af[4], bfr[4];
; #pragma unroll
;     for (int i = 0; i < 4; ++i) af[i] = *(const bf16x8*)(cA + i * 16 * LDS_STRIDE + fo);
; #pragma unroll
;     for (int j = 0; j < 4; ++j) bfr[j] = *(const bf16x8*)(cB + j * 16 * LDS_STRIDE + fo);
; #pragma unroll
;     for (int i = 0; i < 4; ++i)
; #pragma unroll
;       for (int j = 0; j < 4; ++j)
;         acc[i][j] = __builtin_amdgcn_mfma_f32_16x16x32_bf16(bfr[j], af[i], acc[i][j], 0, 0, 0);
;   }
; }
; __device__ __forceinline__ void phase_gemm_merge(const Params& p, char* smem) {
;     ...
;       for (int i = 0; i < 4; ++i) {
;         const int m = mt * 128 + wm * 64 + i * 16 + (lane & 15);
; #pragma unroll
;         for (int j = 0; j < 4; ++j) {
;           const int n = nt * 128 + wn * 64 + j * 16 + (lane >> 4) * 4;
;           const uint2 gz = *(const uint2*)(POST + (size_t)m * POST_W + QC_GATE + b * 1024 + n);
;           outv[i][j][0] += sigmoidf_(bflo(gz.x)) * acc[i][j][0];
;           outv[i][j][1] += sigmoidf_(bfhi(gz.x)) * acc[i][j][1];
;           outv[i][j][2] += sigmoidf_(bflo(gz.y)) * acc[i][j][2];
;           outv[i][j][3] += sigmoidf_(bfhi(gz.y)) * acc[i][j][3];
;         }
	ds_read_b128 v[4:7], v127 offset:16384
	ds_read_b128 v[8:11], v127 offset:18432
	ds_read_b128 v[12:15], v127 offset:20480
	ds_read_b128 v[16:19], v127 offset:22528
	ds_read_b128 v[20:23], v128 offset:49152
	ds_read_b128 v[24:27], v128 offset:51200
	ds_read_b128 v[28:31], v128 offset:53248
	ds_read_b128 v[32:35], v128 offset:55296
	v_mfma_f32_16x16x32_bf16 v[164:167], v[208:211], v[144:147], v[164:167]
	v_mfma_f32_16x16x32_bf16 v[168:171], v[212:215], v[144:147], v[168:171]
	v_mfma_f32_16x16x32_bf16 v[172:175], v[216:219], v[144:147], v[172:175]
	v_mfma_f32_16x16x32_bf16 v[36:39], v[220:223], v[144:147], v[36:39]
	v_mfma_f32_16x16x32_bf16 v[132:135], v[208:211], v[156:159], v[132:135]
	v_mfma_f32_16x16x32_bf16 v[144:147], v[212:215], v[156:159], v[160:163]
	v_mfma_f32_16x16x32_bf16 v[160:163], v[216:219], v[156:159], v[188:191]
	v_mfma_f32_16x16x32_bf16 v[136:139], v[208:211], v[200:203], v[136:139]
	v_mfma_f32_16x16x32_bf16 v[188:191], v[216:219], v[200:203], v[196:199]
	v_mfma_f32_16x16x32_bf16 v[140:143], v[208:211], v[204:207], v[140:143]
	v_mfma_f32_16x16x32_bf16 v[148:151], v[212:215], v[204:207], v[148:151]
	v_mfma_f32_16x16x32_bf16 v[152:155], v[216:219], v[204:207], v[152:155]
	v_mfma_f32_16x16x32_bf16 v[48:51], v[220:223], v[204:207], v[48:51]
	v_mfma_f32_16x16x32_bf16 v[40:43], v[220:223], v[156:159], v[40:43]
	v_mfma_f32_16x16x32_bf16 v[156:159], v[212:215], v[200:203], v[192:195]
	v_mfma_f32_16x16x32_bf16 v[44:47], v[220:223], v[200:203], v[44:47]
	s_waitcnt lgkmcnt(3)
	v_mfma_f32_16x16x32_bf16 v[164:167], v[20:23], v[4:7], v[164:167]
	s_waitcnt lgkmcnt(2)
	v_mfma_f32_16x16x32_bf16 v[168:171], v[24:27], v[4:7], v[168:171]
	s_waitcnt lgkmcnt(1)
	v_mfma_f32_16x16x32_bf16 v[172:175], v[28:31], v[4:7], v[172:175]
	s_waitcnt lgkmcnt(0)
	v_mfma_f32_16x16x32_bf16 v[4:7], v[32:35], v[4:7], v[36:39]
	v_mfma_f32_16x16x32_bf16 v[36:39], v[20:23], v[8:11], v[132:135]
	v_mfma_f32_16x16x32_bf16 v[132:135], v[24:27], v[8:11], v[144:147]
	v_mfma_f32_16x16x32_bf16 v[144:147], v[28:31], v[8:11], v[160:163]
	v_mfma_f32_16x16x32_bf16 v[136:139], v[20:23], v[12:15], v[136:139]
	v_mfma_f32_16x16x32_bf16 v[160:163], v[28:31], v[12:15], v[188:191]
	v_mfma_f32_16x16x32_bf16 v[140:143], v[20:23], v[16:19], v[140:143]
	v_mfma_f32_16x16x32_bf16 v[148:151], v[24:27], v[16:19], v[148:151]
	v_mfma_f32_16x16x32_bf16 v[152:155], v[28:31], v[16:19], v[152:155]
	v_mfma_f32_16x16x32_bf16 v[188:191], v[32:35], v[16:19], v[48:51]
	ds_read_b128 v[16:19], v129 offset:16384
	ds_read_b128 v[20:23], v129 offset:18432
	ds_read_b128 v[192:195], v129 offset:20480
	ds_read_b128 v[126:129], v129 offset:22528
	ds_read_b128 v[196:199], v130 offset:49152
	ds_read_b128 v[200:203], v130 offset:51200
	ds_read_b128 v[204:207], v130 offset:53248
	ds_read_b128 v[208:211], v130 offset:55296
	s_waitcnt lgkmcnt(0)
	s_barrier
	v_mfma_f32_16x16x32_bf16 v[8:11], v[32:35], v[8:11], v[40:43]
	v_mfma_f32_16x16x32_bf16 v[156:159], v[24:27], v[12:15], v[156:159]
	v_mfma_f32_16x16x32_bf16 v[12:15], v[32:35], v[12:15], v[44:47]
	v_mfma_f32_16x16x32_bf16 v[164:167], v[196:199], v[16:19], v[164:167]
	v_mfma_f32_16x16x32_bf16 v[168:171], v[200:203], v[16:19], v[168:171]
	v_mfma_f32_16x16x32_bf16 v[172:175], v[204:207], v[16:19], v[172:175]
	v_mfma_f32_16x16x32_bf16 v[212:215], v[208:211], v[16:19], v[4:7]
	v_mfma_f32_16x16x32_bf16 v[48:51], v[196:199], v[20:23], v[36:39]
	v_mfma_f32_16x16x32_bf16 v[44:47], v[200:203], v[20:23], v[132:135]
	v_mfma_f32_16x16x32_bf16 v[40:43], v[204:207], v[20:23], v[144:147]
	s_nop 1
	v_mov_b32_e32 v133, v166
	v_mov_b32_e32 v166, v165
	v_mov_b32_e32 v132, v164
	v_mfma_f32_16x16x32_bf16 v[36:39], v[208:211], v[20:23], v[8:11]
	v_mfma_f32_16x16x32_bf16 v[20:23], v[208:211], v[192:195], v[12:15]
	v_mfma_f32_16x16x32_bf16 v[16:19], v[196:199], v[126:129], v[140:143]
	v_mfma_f32_16x16x32_bf16 v[12:15], v[200:203], v[126:129], v[148:151]
	v_mfma_f32_16x16x32_bf16 v[8:11], v[204:207], v[126:129], v[152:155]
	v_mfma_f32_16x16x32_bf16 v[4:7], v[208:211], v[126:129], v[188:191]
	v_lshl_add_u64 v[126:127], s[10:11], 0, v[110:111]
	v_add_co_u32_e32 v126, vcc, s59, v126
	v_mfma_f32_16x16x32_bf16 v[32:35], v[196:199], v[192:195], v[136:139]
	s_nop 0
	v_addc_co_u32_e32 v127, vcc, 0, v127, vcc
	s_waitcnt vmcnt(7)
	v_mov_b32_e32 v128, v224
	v_mov_b32_e32 v129, v225
	global_load_dwordx2 v[224:225], v104, s[30:31] offset:3072
	v_mfma_f32_16x16x32_bf16 v[28:31], v[200:203], v[192:195], v[156:159]
	v_lshl_add_u64 v[110:111], v[110:111], 0, s[38:39]
	s_nop 0
	v_lshlrev_b32_e32 v130, 16, v128
	v_and_b32_e32 v128, 0xffff0000, v128
	v_lshlrev_b32_e32 v131, 16, v129
	v_and_b32_e32 v129, 0xffff0000, v129
	v_mul_f32_e32 v128, 0xbfb8aa3b, v128
	v_mul_f32_e32 v129, 0xbfb8aa3b, v129
	v_exp_f32_e32 v128, v128
	v_exp_f32_e32 v129, v129
	v_mul_f32_e32 v130, 0xbfb8aa3b, v130
	v_mul_f32_e32 v131, 0xbfb8aa3b, v131
	v_add_f32_e32 v128, 1.0, v128
	v_add_f32_e32 v129, 1.0, v129
	v_rcp_f32_e32 v128, v128
	v_rcp_f32_e32 v129, v129
	v_exp_f32_e32 v130, v130
	v_exp_f32_e32 v131, v131
	v_mfma_f32_16x16x32_bf16 v[24:27], v[204:207], v[192:195], v[160:163]
	v_fma_f32 v118, v166, v128, v118
	v_fma_f32 v119, v167, v129, v119
	s_waitcnt vmcnt(7)
; __device__ __forceinline__ float bflo(unsigned u) { return __uint_as_float(u << 16); }
; __device__ __forceinline__ float bfhi(unsigned u) { return __uint_as_float(u & 0xffff0000u); }
; __device__ __forceinline__ float sigmoidf_(float x) { return frcp_(1.f + __expf(-x)); }
; __device__ __forceinline__ void phase_gemm_merge(const Params& p, char* smem) {
;     ...
;       for (int i = 0; i < 4; ++i) {
;         const int m = mt * 128 + wm * 64 + i * 16 + (lane & 15);
; #pragma unroll
;         for (int j = 0; j < 4; ++j) {
;           const int n = nt * 128 + wn * 64 + j * 16 + (lane >> 4) * 4;
;           const uint2 gz = *(const uint2*)(POST + (size_t)m * POST_W + QC_GATE + b * 1024 + n);
;           outv[i][j][0] += sigmoidf_(bflo(gz.x)) * acc[i][j][0];
;           outv[i][j][1] += sigmoidf_(bfhi(gz.x)) * acc[i][j][1];
;           outv[i][j][2] += sigmoidf_(bflo(gz.y)) * acc[i][j][2];
;           outv[i][j][3] += sigmoidf_(bfhi(gz.y)) * acc[i][j][3];
;         }
	v_mov_b32_e32 v128, v226
	v_mov_b32_e32 v129, v227
	global_load_dwordx2 v[226:227], v104, s[30:31] offset:3104
	v_add_f32_e32 v130, 1.0, v130
	v_add_f32_e32 v131, 1.0, v131
	v_rcp_f32_e32 v130, v130
	v_rcp_f32_e32 v131, v131
	s_nop 0
	v_pk_fma_f32 v[120:121], v[132:133], v[130:131], v[120:121]
	v_mov_b32_e32 v133, v170
	v_mov_b32_e32 v170, v169
	v_mov_b32_e32 v132, v168
	s_nop 0
	v_lshlrev_b32_e32 v130, 16, v128
	v_and_b32_e32 v128, 0xffff0000, v128
	v_lshlrev_b32_e32 v131, 16, v129
	v_and_b32_e32 v129, 0xffff0000, v129
	v_mul_f32_e32 v128, 0xbfb8aa3b, v128
	v_mul_f32_e32 v129, 0xbfb8aa3b, v129
	v_exp_f32_e32 v128, v128
	v_exp_f32_e32 v129, v129
	v_mul_f32_e32 v130, 0xbfb8aa3b, v130
	v_mul_f32_e32 v131, 0xbfb8aa3b, v131
	v_add_f32_e32 v128, 1.0, v128
	v_add_f32_e32 v129, 1.0, v129
	v_rcp_f32_e32 v128, v128
	v_rcp_f32_e32 v129, v129
	v_exp_f32_e32 v130, v130
	v_exp_f32_e32 v131, v131
	v_pk_fma_f32 v[114:115], v[170:171], v[128:129], v[114:115]
	s_waitcnt vmcnt(7)
	v_mov_b32_e32 v128, v228
	v_mov_b32_e32 v129, v229
	global_load_dwordx2 v[228:229], v104, s[30:31] offset:3136
	v_add_f32_e32 v130, 1.0, v130
	s_waitcnt vmcnt(7)
	v_mov_b32_e32 v126, v230
	v_mov_b32_e32 v127, v231
	global_load_dwordx2 v[230:231], v104, s[30:31] offset:3168
	v_add_f32_e32 v131, 1.0, v131
	v_rcp_f32_e32 v130, v130
	v_rcp_f32_e32 v131, v131
	s_nop 0
	v_pk_fma_f32 v[116:117], v[132:133], v[130:131], v[116:117]
	v_mov_b32_e32 v133, v174
	v_mov_b32_e32 v174, v173
	v_mov_b32_e32 v132, v172
	s_nop 0
	v_lshlrev_b32_e32 v130, 16, v128
	v_and_b32_e32 v128, 0xffff0000, v128
	v_lshlrev_b32_e32 v131, 16, v129
	v_and_b32_e32 v129, 0xffff0000, v129
	v_mul_f32_e32 v128, 0xbfb8aa3b, v128
	v_mul_f32_e32 v129, 0xbfb8aa3b, v129
	v_exp_f32_e32 v128, v128
	v_exp_f32_e32 v129, v129
	v_mul_f32_e32 v130, 0xbfb8aa3b, v130
	v_mul_f32_e32 v131, 0xbfb8aa3b, v131
	v_add_f32_e32 v128, 1.0, v128
	v_add_f32_e32 v129, 1.0, v129
	v_rcp_f32_e32 v128, v128
	v_rcp_f32_e32 v129, v129
	v_exp_f32_e32 v130, v130
	v_exp_f32_e32 v131, v131
	v_pk_fma_f32 v[108:109], v[174:175], v[128:129], v[108:109]
	s_nop 0
	v_lshlrev_b32_e32 v128, 16, v126
	v_and_b32_e32 v126, 0xffff0000, v126
	v_lshlrev_b32_e32 v129, 16, v127
	v_and_b32_e32 v127, 0xffff0000, v127
	v_mul_f32_e32 v126, 0xbfb8aa3b, v126
	v_mul_f32_e32 v127, 0xbfb8aa3b, v127
	v_exp_f32_e32 v126, v126
	v_exp_f32_e32 v127, v127
	v_mul_f32_e32 v128, 0xbfb8aa3b, v128
	v_mul_f32_e32 v129, 0xbfb8aa3b, v129
	v_add_f32_e32 v130, 1.0, v130
	v_add_f32_e32 v131, 1.0, v131
	v_exp_f32_e32 v128, v128
	v_exp_f32_e32 v129, v129
	v_rcp_f32_e32 v130, v130
	v_rcp_f32_e32 v131, v131
	v_add_f32_e32 v126, 1.0, v126
	v_add_f32_e32 v127, 1.0, v127
	v_rcp_f32_e32 v126, v126
	v_rcp_f32_e32 v127, v127
	v_add_f32_e32 v128, 1.0, v128
	v_add_f32_e32 v129, 1.0, v129
	v_pk_fma_f32 v[112:113], v[132:133], v[130:131], v[112:113]
	v_rcp_f32_e32 v128, v128
	v_rcp_f32_e32 v129, v129
	v_mov_b32_e32 v131, v214
	v_mov_b32_e32 v214, v213
	v_pk_fma_f32 v[98:99], v[214:215], v[126:127], v[98:99]
	v_lshl_add_u64 v[126:127], s[10:11], 0, v[106:107]
	v_add_co_u32_e32 v126, vcc, s59, v126
	v_mov_b32_e32 v130, v212
	s_nop 0
	v_addc_co_u32_e32 v127, vcc, 0, v127, vcc
	v_pk_fma_f32 v[100:101], v[130:131], v[128:129], v[100:101]
	s_waitcnt vmcnt(7)
	v_mov_b32_e32 v128, v232
	v_mov_b32_e32 v129, v233
	global_load_dwordx2 v[232:233], v102, s[30:31] offset:3072
	v_mov_b32_e32 v132, v48
	v_mov_b32_e32 v133, v50
	v_mov_b32_e32 v50, v49
	s_waitcnt vmcnt(7)
	v_mov_b32_e32 v48, v234
	v_mov_b32_e32 v49, v235
	global_load_dwordx2 v[234:235], v102, s[30:31] offset:3104
	v_lshl_add_u64 v[106:107], v[106:107], 0, s[38:39]
	s_nop 0
	v_lshlrev_b32_e32 v130, 16, v128
	v_and_b32_e32 v128, 0xffff0000, v128
	v_lshlrev_b32_e32 v131, 16, v129
	v_and_b32_e32 v129, 0xffff0000, v129
	v_mul_f32_e32 v128, 0xbfb8aa3b, v128
	v_mul_f32_e32 v129, 0xbfb8aa3b, v129
	v_exp_f32_e32 v128, v128
	v_exp_f32_e32 v129, v129
	v_mul_f32_e32 v130, 0xbfb8aa3b, v130
	v_mul_f32_e32 v131, 0xbfb8aa3b, v131
	v_add_f32_e32 v128, 1.0, v128
	v_add_f32_e32 v129, 1.0, v129
	v_rcp_f32_e32 v128, v128
	v_rcp_f32_e32 v129, v129
	v_exp_f32_e32 v130, v130
	v_exp_f32_e32 v131, v131
	v_pk_fma_f32 v[94:95], v[50:51], v[128:129], v[94:95]
	s_nop 0
	v_lshlrev_b32_e32 v50, 16, v48
	v_and_b32_e32 v48, 0xffff0000, v48
	v_lshlrev_b32_e32 v51, 16, v49
	v_and_b32_e32 v49, 0xffff0000, v49
	v_mov_b32_e32 v128, v44
	v_mov_b32_e32 v129, v46
	v_mov_b32_e32 v46, v45
	s_waitcnt vmcnt(7)
	v_mov_b32_e32 v44, v236
	v_mov_b32_e32 v45, v237
	global_load_dwordx2 v[236:237], v102, s[30:31] offset:3136
	v_mul_f32_e32 v48, 0xbfb8aa3b, v48
	v_mul_f32_e32 v49, 0xbfb8aa3b, v49
	v_exp_f32_e32 v48, v48
	v_exp_f32_e32 v49, v49
	v_mul_f32_e32 v50, 0xbfb8aa3b, v50
	v_mul_f32_e32 v51, 0xbfb8aa3b, v51
	v_add_f32_e32 v48, 1.0, v48
	v_add_f32_e32 v49, 1.0, v49
	v_rcp_f32_e32 v48, v48
	v_rcp_f32_e32 v49, v49
	v_exp_f32_e32 v50, v50
	v_exp_f32_e32 v51, v51
	v_add_f32_e32 v130, 1.0, v130
	v_pk_fma_f32 v[90:91], v[46:47], v[48:49], v[90:91]
	v_mov_b32_e32 v48, v40
	v_mov_b32_e32 v49, v42
	v_mov_b32_e32 v42, v41
	s_waitcnt vmcnt(7)
; __device__ __forceinline__ float bflo(unsigned u) { return __uint_as_float(u << 16); }
; __device__ __forceinline__ float bfhi(unsigned u) { return __uint_as_float(u & 0xffff0000u); }
; __device__ __forceinline__ float sigmoidf_(float x) { return frcp_(1.f + __expf(-x)); }
; __device__ __forceinline__ void phase_gemm_merge(const Params& p, char* smem) {
;     ...
;       for (int i = 0; i < 4; ++i) {
;         const int m = mt * 128 + wm * 64 + i * 16 + (lane & 15);
; #pragma unroll
;         for (int j = 0; j < 4; ++j) {
;           const int n = nt * 128 + wn * 64 + j * 16 + (lane >> 4) * 4;
;           const uint2 gz = *(const uint2*)(POST + (size_t)m * POST_W + QC_GATE + b * 1024 + n);
;           outv[i][j][0] += sigmoidf_(bflo(gz.x)) * acc[i][j][0];
;           outv[i][j][1] += sigmoidf_(bfhi(gz.x)) * acc[i][j][1];
;           outv[i][j][2] += sigmoidf_(bflo(gz.y)) * acc[i][j][2];
;           outv[i][j][3] += sigmoidf_(bfhi(gz.y)) * acc[i][j][3];
;         }
	v_mov_b32_e32 v40, v238
	v_mov_b32_e32 v41, v239
	global_load_dwordx2 v[238:239], v102, s[30:31] offset:3168
	v_add_f32_e32 v131, 1.0, v131
	v_add_f32_e32 v50, 1.0, v50
	v_add_f32_e32 v51, 1.0, v51
	v_rcp_f32_e32 v130, v130
	v_rcp_f32_e32 v131, v131
	v_rcp_f32_e32 v50, v50
	v_rcp_f32_e32 v51, v51
	v_pk_fma_f32 v[96:97], v[132:133], v[130:131], v[96:97]
	v_pk_fma_f32 v[92:93], v[128:129], v[50:51], v[92:93]
	s_nop 0
	v_lshlrev_b32_e32 v46, 16, v44
	v_and_b32_e32 v44, 0xffff0000, v44
	v_lshlrev_b32_e32 v47, 16, v45
	v_and_b32_e32 v45, 0xffff0000, v45
	v_mul_f32_e32 v44, 0xbfb8aa3b, v44
	v_mul_f32_e32 v45, 0xbfb8aa3b, v45
	v_exp_f32_e32 v44, v44
	v_exp_f32_e32 v45, v45
	v_mul_f32_e32 v46, 0xbfb8aa3b, v46
	v_mul_f32_e32 v47, 0xbfb8aa3b, v47
	v_add_f32_e32 v44, 1.0, v44
	v_add_f32_e32 v45, 1.0, v45
	v_rcp_f32_e32 v44, v44
	v_rcp_f32_e32 v45, v45
	v_exp_f32_e32 v46, v46
	v_exp_f32_e32 v47, v47
	v_pk_fma_f32 v[86:87], v[42:43], v[44:45], v[86:87]
	s_nop 0
	v_lshlrev_b32_e32 v42, 16, v40
	v_and_b32_e32 v40, 0xffff0000, v40
	v_lshlrev_b32_e32 v43, 16, v41
	v_and_b32_e32 v41, 0xffff0000, v41
	v_mul_f32_e32 v40, 0xbfb8aa3b, v40
	v_mul_f32_e32 v41, 0xbfb8aa3b, v41
	v_exp_f32_e32 v40, v40
	v_exp_f32_e32 v41, v41
	v_mov_b32_e32 v44, v36
	v_mov_b32_e32 v45, v38
	v_add_f32_e32 v40, 1.0, v40
	v_add_f32_e32 v41, 1.0, v41
	v_rcp_f32_e32 v40, v40
	v_rcp_f32_e32 v41, v41
	v_mov_b32_e32 v38, v37
	v_lshl_add_u64 v[36:37], s[10:11], 0, v[104:105]
	v_add_co_u32_e32 v36, vcc, s59, v36
	v_pk_fma_f32 v[82:83], v[38:39], v[40:41], v[82:83]
	s_nop 0
	v_addc_co_u32_e32 v37, vcc, 0, v37, vcc
	s_waitcnt vmcnt(7)
	v_mov_b32_e32 v38, v224
	v_mov_b32_e32 v39, v225
	v_mul_f32_e32 v42, 0xbfb8aa3b, v42
	v_mul_f32_e32 v43, 0xbfb8aa3b, v43
	v_exp_f32_e32 v42, v42
	v_exp_f32_e32 v43, v43
	v_add_f32_e32 v46, 1.0, v46
	v_add_f32_e32 v47, 1.0, v47
	v_add_f32_e32 v42, 1.0, v42
	v_add_f32_e32 v43, 1.0, v43
	v_rcp_f32_e32 v42, v42
	v_rcp_f32_e32 v43, v43
	v_rcp_f32_e32 v46, v46
	v_rcp_f32_e32 v47, v47
	v_lshl_add_u64 v[104:105], v[104:105], 0, s[38:39]
	v_pk_fma_f32 v[84:85], v[44:45], v[42:43], v[84:85]
	v_mov_b32_e32 v42, v32
	v_mov_b32_e32 v43, v34
	v_mov_b32_e32 v34, v33
	s_waitcnt vmcnt(6)
	v_mov_b32_e32 v32, v226
	v_mov_b32_e32 v33, v227
	v_pk_fma_f32 v[88:89], v[48:49], v[46:47], v[88:89]
	s_nop 0
	v_lshlrev_b32_e32 v40, 16, v38
	v_and_b32_e32 v38, 0xffff0000, v38
	v_lshlrev_b32_e32 v41, 16, v39
	v_and_b32_e32 v39, 0xffff0000, v39
	v_mul_f32_e32 v38, 0xbfb8aa3b, v38
	v_mul_f32_e32 v39, 0xbfb8aa3b, v39
	v_exp_f32_e32 v38, v38
	v_exp_f32_e32 v39, v39
	v_mul_f32_e32 v40, 0xbfb8aa3b, v40
	v_mul_f32_e32 v41, 0xbfb8aa3b, v41
	v_add_f32_e32 v38, 1.0, v38
	v_add_f32_e32 v39, 1.0, v39
	v_rcp_f32_e32 v38, v38
	v_rcp_f32_e32 v39, v39
	v_exp_f32_e32 v40, v40
	v_exp_f32_e32 v41, v41
	v_pk_fma_f32 v[78:79], v[34:35], v[38:39], v[78:79]
	s_nop 0
	v_lshlrev_b32_e32 v34, 16, v32
	v_and_b32_e32 v32, 0xffff0000, v32
	v_lshlrev_b32_e32 v35, 16, v33
	v_and_b32_e32 v33, 0xffff0000, v33
	v_mov_b32_e32 v38, v28
	v_mov_b32_e32 v39, v30
	v_mov_b32_e32 v30, v29
	s_waitcnt vmcnt(5)
	v_mov_b32_e32 v28, v228
	v_mov_b32_e32 v29, v229
	v_mul_f32_e32 v32, 0xbfb8aa3b, v32
	v_mul_f32_e32 v33, 0xbfb8aa3b, v33
	v_exp_f32_e32 v32, v32
	v_exp_f32_e32 v33, v33
	v_mul_f32_e32 v34, 0xbfb8aa3b, v34
	v_mul_f32_e32 v35, 0xbfb8aa3b, v35
	v_add_f32_e32 v32, 1.0, v32
	v_add_f32_e32 v33, 1.0, v33
	v_rcp_f32_e32 v32, v32
	v_rcp_f32_e32 v33, v33
	v_exp_f32_e32 v34, v34
	v_exp_f32_e32 v35, v35
	v_add_f32_e32 v40, 1.0, v40
	v_pk_fma_f32 v[74:75], v[30:31], v[32:33], v[74:75]
	v_mov_b32_e32 v32, v24
	v_mov_b32_e32 v33, v26
	v_mov_b32_e32 v26, v25
	s_waitcnt vmcnt(4)
	v_mov_b32_e32 v24, v230
	v_mov_b32_e32 v25, v231
	v_add_f32_e32 v41, 1.0, v41
	v_add_f32_e32 v34, 1.0, v34
	v_add_f32_e32 v35, 1.0, v35
	v_rcp_f32_e32 v40, v40
	v_rcp_f32_e32 v41, v41
	v_rcp_f32_e32 v34, v34
	v_rcp_f32_e32 v35, v35
	v_pk_fma_f32 v[80:81], v[42:43], v[40:41], v[80:81]
	v_pk_fma_f32 v[76:77], v[38:39], v[34:35], v[76:77]
	s_nop 0
	v_lshlrev_b32_e32 v30, 16, v28
	v_and_b32_e32 v28, 0xffff0000, v28
	v_lshlrev_b32_e32 v31, 16, v29
	v_and_b32_e32 v29, 0xffff0000, v29
	v_mul_f32_e32 v28, 0xbfb8aa3b, v28
	v_mul_f32_e32 v29, 0xbfb8aa3b, v29
	v_exp_f32_e32 v28, v28
	v_exp_f32_e32 v29, v29
	v_mul_f32_e32 v30, 0xbfb8aa3b, v30
	v_mul_f32_e32 v31, 0xbfb8aa3b, v31
	v_add_f32_e32 v28, 1.0, v28
	v_add_f32_e32 v29, 1.0, v29
	v_rcp_f32_e32 v28, v28
	v_rcp_f32_e32 v29, v29
	v_exp_f32_e32 v30, v30
	v_exp_f32_e32 v31, v31
	v_pk_fma_f32 v[70:71], v[26:27], v[28:29], v[70:71]
	s_nop 0
	v_lshlrev_b32_e32 v26, 16, v24
	v_and_b32_e32 v24, 0xffff0000, v24
	v_lshlrev_b32_e32 v27, 16, v25
	v_and_b32_e32 v25, 0xffff0000, v25
	v_mul_f32_e32 v24, 0xbfb8aa3b, v24
	v_mul_f32_e32 v25, 0xbfb8aa3b, v25
	v_exp_f32_e32 v24, v24
	v_exp_f32_e32 v25, v25
	v_mov_b32_e32 v28, v20
	v_mov_b32_e32 v29, v22
	v_add_f32_e32 v24, 1.0, v24
	v_add_f32_e32 v25, 1.0, v25
	v_rcp_f32_e32 v24, v24
	v_rcp_f32_e32 v25, v25
	v_mov_b32_e32 v22, v21
	v_lshl_add_u64 v[20:21], s[10:11], 0, v[102:103]
	v_add_co_u32_e32 v20, vcc, s59, v20
	v_pk_fma_f32 v[66:67], v[22:23], v[24:25], v[66:67]
	s_nop 0
	v_addc_co_u32_e32 v21, vcc, 0, v21, vcc
	s_waitcnt vmcnt(3)
	v_mov_b32_e32 v22, v232
	v_mov_b32_e32 v23, v233
	v_mul_f32_e32 v26, 0xbfb8aa3b, v26
	v_mul_f32_e32 v27, 0xbfb8aa3b, v27
	v_exp_f32_e32 v26, v26
	v_exp_f32_e32 v27, v27
	v_add_f32_e32 v30, 1.0, v30
	v_add_f32_e32 v31, 1.0, v31
	v_add_f32_e32 v26, 1.0, v26
	v_add_f32_e32 v27, 1.0, v27
	v_rcp_f32_e32 v26, v26
	v_rcp_f32_e32 v27, v27
	v_rcp_f32_e32 v30, v30
	v_rcp_f32_e32 v31, v31
	v_lshl_add_u64 v[102:103], v[102:103], 0, s[38:39]
	v_pk_fma_f32 v[68:69], v[28:29], v[26:27], v[68:69]
	v_mov_b32_e32 v26, v16
	v_mov_b32_e32 v27, v18
	v_mov_b32_e32 v18, v17
	s_waitcnt vmcnt(2)
; __device__ __forceinline__ unsigned pack2(float a, float b) { return (unsigned)f2bf(a) | ((unsigned)f2bf(b) << 16); }
; __device__ __forceinline__ float bflo(unsigned u) { return __uint_as_float(u << 16); }
; __device__ __forceinline__ float bfhi(unsigned u) { return __uint_as_float(u & 0xffff0000u); }
; __device__ __forceinline__ float sigmoidf_(float x) { return frcp_(1.f + __expf(-x)); }
; __device__ __forceinline__ void phase_gemm_merge(const Params& p, char* smem) {
;     ...
;     for (int b = 0; b < 3; ++b) {
;       f32x4 acc[4][4];
; #pragma unroll
;       for (int i = 0; i < 4; ++i)
; #pragma unroll
;         for (int j = 0; j < 4; ++j) acc[i][j] = (f32x4){0.f, 0.f, 0.f, 0.f};
;       gemm_core<false>(BR + (size_t)mt * 128 * 1536 + b * 512, 1536, W + ((size_t)b * 1024 + nt * 128) * 512, 512, 512, acc, smem);
; #pragma unroll
;       for (int i = 0; i < 4; ++i) {
;         const int m = mt * 128 + wm * 64 + i * 16 + (lane & 15);
; #pragma unroll
;         for (int j = 0; j < 4; ++j) {
;           const int n = nt * 128 + wn * 64 + j * 16 + (lane >> 4) * 4;
;           const uint2 gz = *(const uint2*)(POST + (size_t)m * POST_W + QC_GATE + b * 1024 + n);
;           outv[i][j][0] += sigmoidf_(bflo(gz.x)) * acc[i][j][0];
;           outv[i][j][1] += sigmoidf_(bfhi(gz.x)) * acc[i][j][1];
;           outv[i][j][2] += sigmoidf_(bflo(gz.y)) * acc[i][j][2];
;           outv[i][j][3] += sigmoidf_(bfhi(gz.y)) * acc[i][j][3];
;         }
;       }
;     }
; #pragma unroll
;     for (int i = 0; i < 4; ++i) {
;       const int m = mt * 128 + wm * 64 + i * 16 + (lane & 15);
; #pragma unroll
;       for (int j = 0; j < 4; ++j) {
;         const int n = nt * 128 + wn * 64 + j * 16 + (lane >> 4) * 4;
;         uint2 o;
;         o.x = pack2(outv[i][j][0], outv[i][j][1]);
;         o.y = pack2(outv[i][j][2], outv[i][j][3]);
;         *(uint2*)(MG + (size_t)m * 1024 + n) = o;
	v_mov_b32_e32 v16, v234
	v_mov_b32_e32 v17, v235
	v_pk_fma_f32 v[72:73], v[32:33], v[30:31], v[72:73]
	s_nop 0
	v_lshlrev_b32_e32 v24, 16, v22
	v_and_b32_e32 v22, 0xffff0000, v22
	v_lshlrev_b32_e32 v25, 16, v23
	v_and_b32_e32 v23, 0xffff0000, v23
	v_mul_f32_e32 v22, 0xbfb8aa3b, v22
	v_mul_f32_e32 v23, 0xbfb8aa3b, v23
	v_exp_f32_e32 v22, v22
	v_exp_f32_e32 v23, v23
	v_mul_f32_e32 v24, 0xbfb8aa3b, v24
	v_mul_f32_e32 v25, 0xbfb8aa3b, v25
	v_add_f32_e32 v22, 1.0, v22
	v_add_f32_e32 v23, 1.0, v23
	v_rcp_f32_e32 v22, v22
	v_rcp_f32_e32 v23, v23
	v_exp_f32_e32 v24, v24
	v_exp_f32_e32 v25, v25
	v_pk_fma_f32 v[62:63], v[18:19], v[22:23], v[62:63]
	s_nop 0
	v_lshlrev_b32_e32 v18, 16, v16
	v_and_b32_e32 v16, 0xffff0000, v16
	v_lshlrev_b32_e32 v19, 16, v17
	v_and_b32_e32 v17, 0xffff0000, v17
	v_mov_b32_e32 v22, v12
	v_mov_b32_e32 v23, v14
	v_mov_b32_e32 v14, v13
	s_waitcnt vmcnt(1)
	v_mov_b32_e32 v12, v236
	v_mov_b32_e32 v13, v237
	v_mul_f32_e32 v16, 0xbfb8aa3b, v16
	v_mul_f32_e32 v17, 0xbfb8aa3b, v17
	v_exp_f32_e32 v16, v16
	v_exp_f32_e32 v17, v17
	v_mul_f32_e32 v18, 0xbfb8aa3b, v18
	v_mul_f32_e32 v19, 0xbfb8aa3b, v19
	v_add_f32_e32 v16, 1.0, v16
	v_add_f32_e32 v17, 1.0, v17
	v_rcp_f32_e32 v16, v16
	v_rcp_f32_e32 v17, v17
	v_exp_f32_e32 v18, v18
	v_exp_f32_e32 v19, v19
	v_add_f32_e32 v24, 1.0, v24
	v_pk_fma_f32 v[58:59], v[14:15], v[16:17], v[58:59]
	v_mov_b32_e32 v16, v8
	v_mov_b32_e32 v17, v10
	v_mov_b32_e32 v10, v9
	s_waitcnt vmcnt(0)
	v_mov_b32_e32 v8, v238
	v_mov_b32_e32 v9, v239
	v_add_f32_e32 v25, 1.0, v25
	v_add_f32_e32 v18, 1.0, v18
	v_add_f32_e32 v19, 1.0, v19
	v_rcp_f32_e32 v24, v24
	v_rcp_f32_e32 v25, v25
	v_rcp_f32_e32 v18, v18
	v_rcp_f32_e32 v19, v19
	v_pk_fma_f32 v[64:65], v[26:27], v[24:25], v[64:65]
	v_pk_fma_f32 v[60:61], v[22:23], v[18:19], v[60:61]
	s_nop 0
	v_lshlrev_b32_e32 v14, 16, v12
	v_and_b32_e32 v12, 0xffff0000, v12
	v_lshlrev_b32_e32 v15, 16, v13
	v_and_b32_e32 v13, 0xffff0000, v13
	v_mul_f32_e32 v12, 0xbfb8aa3b, v12
	v_mul_f32_e32 v13, 0xbfb8aa3b, v13
	v_exp_f32_e32 v12, v12
	v_exp_f32_e32 v13, v13
	v_mul_f32_e32 v14, 0xbfb8aa3b, v14
	v_mul_f32_e32 v15, 0xbfb8aa3b, v15
	v_add_f32_e32 v12, 1.0, v12
	v_add_f32_e32 v13, 1.0, v13
	v_rcp_f32_e32 v12, v12
	v_rcp_f32_e32 v13, v13
	v_exp_f32_e32 v14, v14
	v_exp_f32_e32 v15, v15
	v_pk_fma_f32 v[54:55], v[10:11], v[12:13], v[54:55]
	s_nop 0
	v_lshlrev_b32_e32 v10, 16, v8
	v_and_b32_e32 v8, 0xffff0000, v8
	v_lshlrev_b32_e32 v11, 16, v9
	v_and_b32_e32 v9, 0xffff0000, v9
	v_mul_f32_e32 v10, 0xbfb8aa3b, v10
	v_mul_f32_e32 v8, 0xbfb8aa3b, v8
	v_mul_f32_e32 v11, 0xbfb8aa3b, v11
	v_mul_f32_e32 v9, 0xbfb8aa3b, v9
	v_exp_f32_e32 v10, v10
	v_exp_f32_e32 v8, v8
	v_exp_f32_e32 v11, v11
	v_exp_f32_e32 v9, v9
	v_add_f32_e32 v14, 1.0, v14
	v_add_f32_e32 v15, 1.0, v15
	v_add_f32_e32 v10, 1.0, v10
	v_add_f32_e32 v8, 1.0, v8
	v_add_f32_e32 v11, 1.0, v11
	v_add_f32_e32 v9, 1.0, v9
	v_rcp_f32_e32 v14, v14
	v_rcp_f32_e32 v15, v15
	v_rcp_f32_e32 v10, v10
	v_rcp_f32_e32 v8, v8
	v_rcp_f32_e32 v11, v11
	v_rcp_f32_e32 v9, v9
	v_mov_b32_e32 v12, v4
	v_mov_b32_e32 v13, v6
	v_mov_b32_e32 v6, v5
	v_pk_fma_f32 v[56:57], v[16:17], v[14:15], v[56:57]
	v_pk_fma_f32 v[0:1], v[12:13], v[10:11], v[0:1]
	v_pk_fma_f32 v[52:53], v[6:7], v[8:9], v[52:53]
	s_cmpk_eq_i32 s16, 0xc00
	s_cbranch_scc0 .LBB0_21
	v_lshl_add_u32 v4, s27, 7, v2
	v_and_b32_sdwa v15, v120, v183 dst_sel:DWORD dst_unused:UNUSED_PAD src0_sel:WORD_1 src1_sel:DWORD
	v_or_b32_e32 v6, s12, v122
	v_ashrrev_i32_e32 v5, 31, v4
	v_readlane_b32 s12, v244, 7
	v_add3_u32 v16, v120, v15, s37
	v_and_b32_sdwa v15, v119, v183 dst_sel:DWORD dst_unused:UNUSED_PAD src0_sel:WORD_1 src1_sel:DWORD
	v_and_b32_sdwa v17, v118, v183 dst_sel:DWORD dst_unused:UNUSED_PAD src0_sel:WORD_1 src1_sel:DWORD
	v_or_b32_e32 v8, 48, v4
	v_ashrrev_i32_e32 v7, 31, v6
	v_or_b32_e32 v10, 16, v4
	v_or_b32_e32 v12, 32, v4
	v_lshlrev_b64 v[4:5], 11, v[4:5]
	v_readlane_b32 s13, v244, 8
	v_and_b32_sdwa v14, v121, v183 dst_sel:DWORD dst_unused:UNUSED_PAD src0_sel:WORD_1 src1_sel:DWORD
	v_add3_u32 v15, v119, v15, s37
	v_add3_u32 v17, v118, v17, s37
	v_lshl_add_u64 v[4:5], s[12:13], 0, v[4:5]
	v_lshlrev_b64 v[6:7], 1, v[6:7]
	v_add3_u32 v14, v121, v14, s37
	v_and_b32_e32 v15, 0xffff0000, v15
	v_and_b32_e32 v17, 0xffff0000, v17
	v_lshl_add_u64 v[4:5], v[4:5], 0, v[6:7]
	v_or_b32_sdwa v15, v15, v14 dst_sel:DWORD dst_unused:UNUSED_PAD src0_sel:DWORD src1_sel:WORD_1
	v_or_b32_sdwa v14, v17, v16 dst_sel:DWORD dst_unused:UNUSED_PAD src0_sel:DWORD src1_sel:WORD_1
	global_store_dwordx2 v[4:5], v[14:15], off
	v_and_b32_sdwa v15, v116, v183 dst_sel:DWORD dst_unused:UNUSED_PAD src0_sel:WORD_1 src1_sel:DWORD
	v_add3_u32 v16, v116, v15, s37
	v_and_b32_sdwa v15, v115, v183 dst_sel:DWORD dst_unused:UNUSED_PAD src0_sel:WORD_1 src1_sel:DWORD
	v_and_b32_sdwa v17, v114, v183 dst_sel:DWORD dst_unused:UNUSED_PAD src0_sel:WORD_1 src1_sel:DWORD
	v_and_b32_sdwa v14, v117, v183 dst_sel:DWORD dst_unused:UNUSED_PAD src0_sel:WORD_1 src1_sel:DWORD
	v_add3_u32 v15, v115, v15, s37
	v_add3_u32 v17, v114, v17, s37
	v_add3_u32 v14, v117, v14, s37
	v_and_b32_e32 v15, 0xffff0000, v15
	v_and_b32_e32 v17, 0xffff0000, v17
	v_or_b32_sdwa v15, v15, v14 dst_sel:DWORD dst_unused:UNUSED_PAD src0_sel:DWORD src1_sel:WORD_1
	v_or_b32_sdwa v14, v17, v16 dst_sel:DWORD dst_unused:UNUSED_PAD src0_sel:DWORD src1_sel:WORD_1
	global_store_dwordx2 v[4:5], v[14:15], off offset:32
	v_and_b32_sdwa v15, v112, v183 dst_sel:DWORD dst_unused:UNUSED_PAD src0_sel:WORD_1 src1_sel:DWORD
	v_add3_u32 v16, v112, v15, s37
	v_and_b32_sdwa v15, v109, v183 dst_sel:DWORD dst_unused:UNUSED_PAD src0_sel:WORD_1 src1_sel:DWORD
; __device__ __forceinline__ unsigned pack2(float a, float b) { return (unsigned)f2bf(a) | ((unsigned)f2bf(b) << 16); }
; __device__ __forceinline__ void phase_gemm_merge(const Params& p, char* smem) {
;     ...
; #pragma unroll
;     for (int i = 0; i < 4; ++i) {
;       const int m = mt * 128 + wm * 64 + i * 16 + (lane & 15);
; #pragma unroll
;       for (int j = 0; j < 4; ++j) {
;         const int n = nt * 128 + wn * 64 + j * 16 + (lane >> 4) * 4;
;         uint2 o;
;         o.x = pack2(outv[i][j][0], outv[i][j][1]);
;         o.y = pack2(outv[i][j][2], outv[i][j][3]);
;         *(uint2*)(MG + (size_t)m * 1024 + n) = o;
;       }
	v_and_b32_sdwa v17, v108, v183 dst_sel:DWORD dst_unused:UNUSED_PAD src0_sel:WORD_1 src1_sel:DWORD
	v_and_b32_sdwa v14, v113, v183 dst_sel:DWORD dst_unused:UNUSED_PAD src0_sel:WORD_1 src1_sel:DWORD
	v_add3_u32 v15, v109, v15, s37
	v_add3_u32 v17, v108, v17, s37
	v_add3_u32 v14, v113, v14, s37
	v_and_b32_e32 v15, 0xffff0000, v15
	v_and_b32_e32 v17, 0xffff0000, v17
	v_or_b32_sdwa v15, v15, v14 dst_sel:DWORD dst_unused:UNUSED_PAD src0_sel:DWORD src1_sel:WORD_1
	v_or_b32_sdwa v14, v17, v16 dst_sel:DWORD dst_unused:UNUSED_PAD src0_sel:DWORD src1_sel:WORD_1
	global_store_dwordx2 v[4:5], v[14:15], off offset:64
	v_and_b32_sdwa v15, v100, v183 dst_sel:DWORD dst_unused:UNUSED_PAD src0_sel:WORD_1 src1_sel:DWORD
	v_add3_u32 v16, v100, v15, s37
	v_and_b32_sdwa v15, v99, v183 dst_sel:DWORD dst_unused:UNUSED_PAD src0_sel:WORD_1 src1_sel:DWORD
	v_and_b32_sdwa v17, v98, v183 dst_sel:DWORD dst_unused:UNUSED_PAD src0_sel:WORD_1 src1_sel:DWORD
	v_and_b32_sdwa v14, v101, v183 dst_sel:DWORD dst_unused:UNUSED_PAD src0_sel:WORD_1 src1_sel:DWORD
	v_add3_u32 v15, v99, v15, s37
	v_add3_u32 v17, v98, v17, s37
	v_add3_u32 v14, v101, v14, s37
	v_and_b32_e32 v15, 0xffff0000, v15
	v_and_b32_e32 v17, 0xffff0000, v17
	v_ashrrev_i32_e32 v11, 31, v10
	v_or_b32_sdwa v15, v15, v14 dst_sel:DWORD dst_unused:UNUSED_PAD src0_sel:DWORD src1_sel:WORD_1
	v_or_b32_sdwa v14, v17, v16 dst_sel:DWORD dst_unused:UNUSED_PAD src0_sel:DWORD src1_sel:WORD_1
	global_store_dwordx2 v[4:5], v[14:15], off offset:96
	v_lshlrev_b64 v[4:5], 11, v[10:11]
	v_and_b32_sdwa v11, v96, v183 dst_sel:DWORD dst_unused:UNUSED_PAD src0_sel:WORD_1 src1_sel:DWORD
	v_add3_u32 v14, v96, v11, s37
	v_and_b32_sdwa v11, v95, v183 dst_sel:DWORD dst_unused:UNUSED_PAD src0_sel:WORD_1 src1_sel:DWORD
	v_and_b32_sdwa v15, v94, v183 dst_sel:DWORD dst_unused:UNUSED_PAD src0_sel:WORD_1 src1_sel:DWORD
	v_and_b32_sdwa v10, v97, v183 dst_sel:DWORD dst_unused:UNUSED_PAD src0_sel:WORD_1 src1_sel:DWORD
	v_add3_u32 v11, v95, v11, s37
	v_add3_u32 v15, v94, v15, s37
	v_lshl_add_u64 v[4:5], s[12:13], 0, v[4:5]
	v_add3_u32 v10, v97, v10, s37
	v_and_b32_e32 v11, 0xffff0000, v11
	v_and_b32_e32 v15, 0xffff0000, v15
	v_lshl_add_u64 v[4:5], v[4:5], 0, v[6:7]
	v_or_b32_sdwa v11, v11, v10 dst_sel:DWORD dst_unused:UNUSED_PAD src0_sel:DWORD src1_sel:WORD_1
	v_or_b32_sdwa v10, v15, v14 dst_sel:DWORD dst_unused:UNUSED_PAD src0_sel:DWORD src1_sel:WORD_1
	global_store_dwordx2 v[4:5], v[10:11], off
	v_and_b32_sdwa v11, v92, v183 dst_sel:DWORD dst_unused:UNUSED_PAD src0_sel:WORD_1 src1_sel:DWORD
	v_add3_u32 v14, v92, v11, s37
	v_and_b32_sdwa v11, v91, v183 dst_sel:DWORD dst_unused:UNUSED_PAD src0_sel:WORD_1 src1_sel:DWORD
	v_and_b32_sdwa v15, v90, v183 dst_sel:DWORD dst_unused:UNUSED_PAD src0_sel:WORD_1 src1_sel:DWORD
	v_and_b32_sdwa v10, v93, v183 dst_sel:DWORD dst_unused:UNUSED_PAD src0_sel:WORD_1 src1_sel:DWORD
	v_add3_u32 v11, v91, v11, s37
	v_add3_u32 v15, v90, v15, s37
	v_add3_u32 v10, v93, v10, s37
	v_and_b32_e32 v11, 0xffff0000, v11
	v_and_b32_e32 v15, 0xffff0000, v15
	v_or_b32_sdwa v11, v11, v10 dst_sel:DWORD dst_unused:UNUSED_PAD src0_sel:DWORD src1_sel:WORD_1
	v_or_b32_sdwa v10, v15, v14 dst_sel:DWORD dst_unused:UNUSED_PAD src0_sel:DWORD src1_sel:WORD_1
	global_store_dwordx2 v[4:5], v[10:11], off offset:32
	v_and_b32_sdwa v11, v88, v183 dst_sel:DWORD dst_unused:UNUSED_PAD src0_sel:WORD_1 src1_sel:DWORD
	v_add3_u32 v14, v88, v11, s37
	v_and_b32_sdwa v11, v87, v183 dst_sel:DWORD dst_unused:UNUSED_PAD src0_sel:WORD_1 src1_sel:DWORD
	v_and_b32_sdwa v15, v86, v183 dst_sel:DWORD dst_unused:UNUSED_PAD src0_sel:WORD_1 src1_sel:DWORD
	v_and_b32_sdwa v10, v89, v183 dst_sel:DWORD dst_unused:UNUSED_PAD src0_sel:WORD_1 src1_sel:DWORD
	v_add3_u32 v11, v87, v11, s37
	v_add3_u32 v15, v86, v15, s37
	v_add3_u32 v10, v89, v10, s37
	v_and_b32_e32 v11, 0xffff0000, v11
	v_and_b32_e32 v15, 0xffff0000, v15
	v_or_b32_sdwa v11, v11, v10 dst_sel:DWORD dst_unused:UNUSED_PAD src0_sel:DWORD src1_sel:WORD_1
	v_or_b32_sdwa v10, v15, v14 dst_sel:DWORD dst_unused:UNUSED_PAD src0_sel:DWORD src1_sel:WORD_1
	global_store_dwordx2 v[4:5], v[10:11], off offset:64
	v_and_b32_sdwa v11, v84, v183 dst_sel:DWORD dst_unused:UNUSED_PAD src0_sel:WORD_1 src1_sel:DWORD
	v_add3_u32 v14, v84, v11, s37
	v_and_b32_sdwa v11, v83, v183 dst_sel:DWORD dst_unused:UNUSED_PAD src0_sel:WORD_1 src1_sel:DWORD
	v_and_b32_sdwa v15, v82, v183 dst_sel:DWORD dst_unused:UNUSED_PAD src0_sel:WORD_1 src1_sel:DWORD
	v_and_b32_sdwa v10, v85, v183 dst_sel:DWORD dst_unused:UNUSED_PAD src0_sel:WORD_1 src1_sel:DWORD
	v_add3_u32 v11, v83, v11, s37
	v_add3_u32 v15, v82, v15, s37
	v_add3_u32 v10, v85, v10, s37
	v_and_b32_e32 v11, 0xffff0000, v11
	v_and_b32_e32 v15, 0xffff0000, v15
	v_or_b32_sdwa v11, v11, v10 dst_sel:DWORD dst_unused:UNUSED_PAD src0_sel:DWORD src1_sel:WORD_1
	v_or_b32_sdwa v10, v15, v14 dst_sel:DWORD dst_unused:UNUSED_PAD src0_sel:DWORD src1_sel:WORD_1
	v_ashrrev_i32_e32 v13, 31, v12
	global_store_dwordx2 v[4:5], v[10:11], off offset:96
	v_and_b32_sdwa v11, v80, v183 dst_sel:DWORD dst_unused:UNUSED_PAD src0_sel:WORD_1 src1_sel:DWORD
	v_lshlrev_b64 v[4:5], 11, v[12:13]
	v_add3_u32 v12, v80, v11, s37
	v_and_b32_sdwa v11, v79, v183 dst_sel:DWORD dst_unused:UNUSED_PAD src0_sel:WORD_1 src1_sel:DWORD
	v_and_b32_sdwa v13, v78, v183 dst_sel:DWORD dst_unused:UNUSED_PAD src0_sel:WORD_1 src1_sel:DWORD
	v_and_b32_sdwa v10, v81, v183 dst_sel:DWORD dst_unused:UNUSED_PAD src0_sel:WORD_1 src1_sel:DWORD
	v_add3_u32 v11, v79, v11, s37
	v_add3_u32 v13, v78, v13, s37
	v_lshl_add_u64 v[4:5], s[12:13], 0, v[4:5]
	v_add3_u32 v10, v81, v10, s37
	v_and_b32_e32 v11, 0xffff0000, v11
	v_and_b32_e32 v13, 0xffff0000, v13
; __device__ __forceinline__ unsigned pack2(float a, float b) { return (unsigned)f2bf(a) | ((unsigned)f2bf(b) << 16); }
; __device__ __forceinline__ void phase_gemm_merge(const Params& p, char* smem) {
;     ...
; #pragma unroll
;     for (int i = 0; i < 4; ++i) {
;       const int m = mt * 128 + wm * 64 + i * 16 + (lane & 15);
; #pragma unroll
;       for (int j = 0; j < 4; ++j) {
;         const int n = nt * 128 + wn * 64 + j * 16 + (lane >> 4) * 4;
;         uint2 o;
;         o.x = pack2(outv[i][j][0], outv[i][j][1]);
;         o.y = pack2(outv[i][j][2], outv[i][j][3]);
;         *(uint2*)(MG + (size_t)m * 1024 + n) = o;
;       }
;     }
;   }
	v_lshl_add_u64 v[4:5], v[4:5], 0, v[6:7]
	v_or_b32_sdwa v11, v11, v10 dst_sel:DWORD dst_unused:UNUSED_PAD src0_sel:DWORD src1_sel:WORD_1
	v_or_b32_sdwa v10, v13, v12 dst_sel:DWORD dst_unused:UNUSED_PAD src0_sel:DWORD src1_sel:WORD_1
	global_store_dwordx2 v[4:5], v[10:11], off
	v_and_b32_sdwa v11, v76, v183 dst_sel:DWORD dst_unused:UNUSED_PAD src0_sel:WORD_1 src1_sel:DWORD
	v_add3_u32 v12, v76, v11, s37
	v_and_b32_sdwa v11, v75, v183 dst_sel:DWORD dst_unused:UNUSED_PAD src0_sel:WORD_1 src1_sel:DWORD
	v_and_b32_sdwa v13, v74, v183 dst_sel:DWORD dst_unused:UNUSED_PAD src0_sel:WORD_1 src1_sel:DWORD
	v_and_b32_sdwa v10, v77, v183 dst_sel:DWORD dst_unused:UNUSED_PAD src0_sel:WORD_1 src1_sel:DWORD
	v_add3_u32 v11, v75, v11, s37
	v_add3_u32 v13, v74, v13, s37
	v_add3_u32 v10, v77, v10, s37
	v_and_b32_e32 v11, 0xffff0000, v11
	v_and_b32_e32 v13, 0xffff0000, v13
	v_or_b32_sdwa v11, v11, v10 dst_sel:DWORD dst_unused:UNUSED_PAD src0_sel:DWORD src1_sel:WORD_1
	v_or_b32_sdwa v10, v13, v12 dst_sel:DWORD dst_unused:UNUSED_PAD src0_sel:DWORD src1_sel:WORD_1
	global_store_dwordx2 v[4:5], v[10:11], off offset:32
	v_and_b32_sdwa v11, v72, v183 dst_sel:DWORD dst_unused:UNUSED_PAD src0_sel:WORD_1 src1_sel:DWORD
	v_add3_u32 v12, v72, v11, s37
	v_and_b32_sdwa v11, v71, v183 dst_sel:DWORD dst_unused:UNUSED_PAD src0_sel:WORD_1 src1_sel:DWORD
	v_and_b32_sdwa v13, v70, v183 dst_sel:DWORD dst_unused:UNUSED_PAD src0_sel:WORD_1 src1_sel:DWORD
	v_and_b32_sdwa v10, v73, v183 dst_sel:DWORD dst_unused:UNUSED_PAD src0_sel:WORD_1 src1_sel:DWORD
	v_add3_u32 v11, v71, v11, s37
	v_add3_u32 v13, v70, v13, s37
	v_add3_u32 v10, v73, v10, s37
	v_and_b32_e32 v11, 0xffff0000, v11
	v_and_b32_e32 v13, 0xffff0000, v13
	v_or_b32_sdwa v11, v11, v10 dst_sel:DWORD dst_unused:UNUSED_PAD src0_sel:DWORD src1_sel:WORD_1
	v_or_b32_sdwa v10, v13, v12 dst_sel:DWORD dst_unused:UNUSED_PAD src0_sel:DWORD src1_sel:WORD_1
	global_store_dwordx2 v[4:5], v[10:11], off offset:64
	v_and_b32_sdwa v11, v68, v183 dst_sel:DWORD dst_unused:UNUSED_PAD src0_sel:WORD_1 src1_sel:DWORD
	v_add3_u32 v12, v68, v11, s37
	v_and_b32_sdwa v11, v67, v183 dst_sel:DWORD dst_unused:UNUSED_PAD src0_sel:WORD_1 src1_sel:DWORD
	v_and_b32_sdwa v13, v66, v183 dst_sel:DWORD dst_unused:UNUSED_PAD src0_sel:WORD_1 src1_sel:DWORD
	v_and_b32_sdwa v10, v69, v183 dst_sel:DWORD dst_unused:UNUSED_PAD src0_sel:WORD_1 src1_sel:DWORD
	v_add3_u32 v11, v67, v11, s37
	v_add3_u32 v13, v66, v13, s37
	v_add3_u32 v10, v69, v10, s37
	v_and_b32_e32 v11, 0xffff0000, v11
	v_and_b32_e32 v13, 0xffff0000, v13
	v_ashrrev_i32_e32 v9, 31, v8
	v_or_b32_sdwa v11, v11, v10 dst_sel:DWORD dst_unused:UNUSED_PAD src0_sel:DWORD src1_sel:WORD_1
	v_or_b32_sdwa v10, v13, v12 dst_sel:DWORD dst_unused:UNUSED_PAD src0_sel:DWORD src1_sel:WORD_1
	global_store_dwordx2 v[4:5], v[10:11], off offset:96
	v_lshlrev_b64 v[4:5], 11, v[8:9]
	v_lshl_add_u64 v[4:5], s[12:13], 0, v[4:5]
	v_lshl_add_u64 v[4:5], v[4:5], 0, v[6:7]
	v_and_b32_sdwa v7, v64, v183 dst_sel:DWORD dst_unused:UNUSED_PAD src0_sel:WORD_1 src1_sel:DWORD
	v_add3_u32 v8, v64, v7, s37
	v_and_b32_sdwa v7, v63, v183 dst_sel:DWORD dst_unused:UNUSED_PAD src0_sel:WORD_1 src1_sel:DWORD
	v_and_b32_sdwa v9, v62, v183 dst_sel:DWORD dst_unused:UNUSED_PAD src0_sel:WORD_1 src1_sel:DWORD
	v_and_b32_sdwa v6, v65, v183 dst_sel:DWORD dst_unused:UNUSED_PAD src0_sel:WORD_1 src1_sel:DWORD
	v_add3_u32 v7, v63, v7, s37
	v_add3_u32 v9, v62, v9, s37
	v_add3_u32 v6, v65, v6, s37
	v_and_b32_e32 v7, 0xffff0000, v7
	v_and_b32_e32 v9, 0xffff0000, v9
	v_or_b32_sdwa v7, v7, v6 dst_sel:DWORD dst_unused:UNUSED_PAD src0_sel:DWORD src1_sel:WORD_1
	v_or_b32_sdwa v6, v9, v8 dst_sel:DWORD dst_unused:UNUSED_PAD src0_sel:DWORD src1_sel:WORD_1
	global_store_dwordx2 v[4:5], v[6:7], off
	v_and_b32_sdwa v7, v60, v183 dst_sel:DWORD dst_unused:UNUSED_PAD src0_sel:WORD_1 src1_sel:DWORD
	v_add3_u32 v8, v60, v7, s37
	v_and_b32_sdwa v7, v59, v183 dst_sel:DWORD dst_unused:UNUSED_PAD src0_sel:WORD_1 src1_sel:DWORD
	v_and_b32_sdwa v9, v58, v183 dst_sel:DWORD dst_unused:UNUSED_PAD src0_sel:WORD_1 src1_sel:DWORD
	v_and_b32_sdwa v6, v61, v183 dst_sel:DWORD dst_unused:UNUSED_PAD src0_sel:WORD_1 src1_sel:DWORD
	v_add3_u32 v7, v59, v7, s37
	v_add3_u32 v9, v58, v9, s37
	v_add3_u32 v6, v61, v6, s37
	v_and_b32_e32 v7, 0xffff0000, v7
	v_and_b32_e32 v9, 0xffff0000, v9
	v_or_b32_sdwa v7, v7, v6 dst_sel:DWORD dst_unused:UNUSED_PAD src0_sel:DWORD src1_sel:WORD_1
	v_or_b32_sdwa v6, v9, v8 dst_sel:DWORD dst_unused:UNUSED_PAD src0_sel:DWORD src1_sel:WORD_1
	global_store_dwordx2 v[4:5], v[6:7], off offset:32
	v_and_b32_sdwa v7, v56, v183 dst_sel:DWORD dst_unused:UNUSED_PAD src0_sel:WORD_1 src1_sel:DWORD
	v_add3_u32 v8, v56, v7, s37
	v_and_b32_sdwa v7, v55, v183 dst_sel:DWORD dst_unused:UNUSED_PAD src0_sel:WORD_1 src1_sel:DWORD
	v_and_b32_sdwa v9, v54, v183 dst_sel:DWORD dst_unused:UNUSED_PAD src0_sel:WORD_1 src1_sel:DWORD
	v_and_b32_sdwa v6, v57, v183 dst_sel:DWORD dst_unused:UNUSED_PAD src0_sel:WORD_1 src1_sel:DWORD
	v_add3_u32 v7, v55, v7, s37
	v_add3_u32 v9, v54, v9, s37
	v_add3_u32 v6, v57, v6, s37
	v_and_b32_e32 v7, 0xffff0000, v7
	v_and_b32_e32 v9, 0xffff0000, v9
	v_or_b32_sdwa v7, v7, v6 dst_sel:DWORD dst_unused:UNUSED_PAD src0_sel:DWORD src1_sel:WORD_1
	v_or_b32_sdwa v6, v9, v8 dst_sel:DWORD dst_unused:UNUSED_PAD src0_sel:DWORD src1_sel:WORD_1
	global_store_dwordx2 v[4:5], v[6:7], off offset:64
	v_and_b32_sdwa v6, v1, v183 dst_sel:DWORD dst_unused:UNUSED_PAD src0_sel:WORD_1 src1_sel:DWORD
	v_and_b32_sdwa v7, v0, v183 dst_sel:DWORD dst_unused:UNUSED_PAD src0_sel:WORD_1 src1_sel:DWORD
	v_add3_u32 v0, v0, v7, s37
	v_add3_u32 v1, v1, v6, s37
	v_and_b32_sdwa v6, v53, v183 dst_sel:DWORD dst_unused:UNUSED_PAD src0_sel:WORD_1 src1_sel:DWORD
	v_and_b32_sdwa v7, v52, v183 dst_sel:DWORD dst_unused:UNUSED_PAD src0_sel:WORD_1 src1_sel:DWORD
	v_add3_u32 v6, v53, v6, s37
	v_add3_u32 v7, v52, v7, s37
	s_add_i32 s24, s24, 1
	v_and_b32_e32 v6, 0xffff0000, v6
	v_and_b32_e32 v7, 0xffff0000, v7
	s_cmp_eq_u32 s24, s22
	v_or_b32_sdwa v1, v6, v1 dst_sel:DWORD dst_unused:UNUSED_PAD src0_sel:DWORD src1_sel:WORD_1
	v_or_b32_sdwa v0, v7, v0 dst_sel:DWORD dst_unused:UNUSED_PAD src0_sel:DWORD src1_sel:WORD_1
	s_cselect_b64 s[12:13], -1, 0
	s_mov_b32 s31, 0x18000
	global_store_dwordx2 v[4:5], v[0:1], off offset:96
	s_branch .LBB0_18
